# attention MFMAs reordered (t-outer K fragments, snake qb order) so consecutive MFMAs share an operand
# speedup vs baseline: 1.0720x; 1.0109x over previous
; __device__ __forceinline__ int opaque_tid() { int t = threadIdx.x; asm volatile("" : "+v"(t)); return t; }
; __device__ __forceinline__ int v_st(int k, int c) { const int kk = (k & ~0xC) | ((k & 4) << 1) | ((k & 8) >> 1); return ((kk >> 3) * 4 + (c >> 5)) * 512 + ((kk & 7) * 32 + (c & 31)) * 2; }
; __device__ __forceinline__ int v_rd_base(int lane) { return ((lane & 3) << 3) | (((lane >> 2) & 3) << 6) | (((lane >> 4) & 1) << 5) | (((lane >> 5) & 1) << 8); }
; __device__ __forceinline__ void attn_unit(const bf16_t* __restrict__ Qb, const bf16_t* __restrict__ Kn, const bf16_t* __restrict__ Kr, const bf16_t* __restrict__ Vh,
;                                           bf16_t* __restrict__ Ob, char* lds) {
;   const int tid = opaque_tid(), wid = tid >> 6, lane = tid & 63, r32 = lane & 31, hi = lane >> 5;
;   char* V_lds = lds; char* K_lds = lds + 2 * SHM_V;
;   float* ws = (float*)(lds + 2 * SHM_V + 2 * SHM_K) + wid * 64; float* li_l = ws; float* al_l = ws + 32;
;   float m_reg = 0.f, l_reg = 0; f32x16 o[4] = {}; bf16x8 qr[8];
;   char* qL = lds + 2 * SHM_V + 2 * SHM_K + 2048 + wid * 4096 + lane * 16;
;   const bf16_t* Qw = Qb + (long)(wid * 32 + r32) * 192 + hi * 8;
; #pragma unroll
;   for (int d0 = 0; d0 < 8; ++d0) qr[d0] = *reinterpret_cast<const bf16x8*>(Qw + d0 * 16);
; #pragma unroll
;   for (int d0 = 8; d0 < 12; ++d0) *reinterpret_cast<bf16x8*>(qL + (d0 - 8) * 1024) = *reinterpret_cast<const bf16x8*>(Qw + d0 * 16);
;   const int sr = tid >> 4, sc = (tid & 15) * 8, vst0 = v_st(sr, sc), vst1 = v_st(32 + sr, sc);
;   const int rr = tid >> 3, rc = (tid & 7) * 8;
;   const int kst0 = KSWZ(sr, sc * 2), kst1 = KSWZ(32 + sr, sc * 2), kst2 = KSWZ(rr, 256 + rc * 2);
;   const int vb0 = (int)(uintptr_t)V_lds + v_rd_base(lane);
;   struct { bf16x8 vs0, vs1, ks0, ks1, ks2; } sr_[SDEPTH];
;     ...
;   f32x16 pA0, pA1, pB0, pB1; float alA, alB; bf16x8 pa0, pa1, pa2, pa3; const int NT = T / KVBLK;
;   constexpr int SE = 0, SO = SDEPTH - 1;
;   SLOAD(SE, 0); asm volatile("s_waitcnt vmcnt(0)" ::: "memory"); SWRITE(0, SE); __syncthreads();
;   qkt(pA0, pA1, K_lds, qr, qL, r32, hi, 0.f); partialSM<true>(pA0, pA1, m_reg, alA);
.LBB0_465:
.LBB0_466:
	s_mul_i32 s41, s16, 0x18000
	s_mul_hi_u32 s42, s16, 0x18000
	s_add_u32 s20, s68, s28
	s_addc_u32 s21, s69, s5
	s_add_u32 s20, s20, s41
	s_addc_u32 s21, s21, s42
	s_add_u32 s20, s20, 0x23300000
	s_addc_u32 s21, s21, 0
	s_add_u32 s22, s68, s14
	s_addc_u32 s23, s69, s15
	s_add_u32 s26, s22, 0x2d300000
	s_addc_u32 s27, s23, 0
	s_add_u32 s22, s22, 0x29300000
	s_addc_u32 s23, s23, 0
	s_add_u32 s24, s22, 8192
	s_addc_u32 s25, s23, 0
	s_add_u32 s30, s26, 8192
	s_addc_u32 s31, s27, 0
	s_add_u32 s34, s68, s8
	s_addc_u32 s35, s69, s9
	s_add_u32 s34, s34, 0x31300000
	s_addc_u32 s35, s35, 0
	s_lshl_b32 s41, s16, 20
	s_add_u32 s36, s68, s10
	s_addc_u32 s37, s69, s11
	s_add_u32 s36, s36, s41
	s_addc_u32 s37, s37, 0
	s_add_u32 s36, s36, s29
	s_addc_u32 s37, s37, 0
	s_add_u32 s36, s36, 0x6300800
	s_addc_u32 s37, s37, 0
	s_mov_b32 s38, 0x4138aa3b
	v_and_b32_e32 v235, 63, v195
	v_lshrrev_b32_e32 v243, 6, v195
	v_lshlrev_b32_e32 v218, 4, v195
	v_readfirstlane_b32 s40, v243
	v_and_b32_e32 v244, 15, v235
	v_lshrrev_b32_e32 v245, 4, v235
	global_load_dwordx4 v[178:181], v218, s[22:23]
	global_load_dwordx4 v[182:185], v218, s[24:25]
	global_load_dwordx4 v[196:199], v218, s[34:35]
	global_load_dwordx4 v[186:189], v218, s[26:27]
	global_load_dwordx4 v[190:193], v218, s[30:31]
	s_add_u32 s22, s22, 16384
	s_addc_u32 s23, s23, 0
	s_add_u32 s24, s24, 16384
	s_addc_u32 s25, s25, 0
	s_add_u32 s26, s26, 16384
	s_addc_u32 s27, s27, 0
	s_add_u32 s30, s30, 16384
	s_addc_u32 s31, s31, 0
	s_add_u32 s34, s34, 8192
	s_addc_u32 s35, s35, 0
	s_mul_i32 s41, s40, 0x3000
	s_add_u32 s20, s20, s41
	s_addc_u32 s21, s21, 0
	s_lshl_b32 s41, s40, 17
	s_add_u32 s36, s36, s41
	s_addc_u32 s37, s37, 0
	v_mul_u32_u24_e32 v246, 0x180, v244
	v_lshl_add_u32 v246, v245, 4, v246
	v_add_u32_e32 v247, 0x1800, v246
	global_load_dwordx4 v[64:67], v246, s[20:21] offset:0
	global_load_dwordx4 v[68:71], v246, s[20:21] offset:64
	global_load_dwordx4 v[72:75], v246, s[20:21] offset:128
	global_load_dwordx4 v[76:79], v246, s[20:21] offset:192
	global_load_dwordx4 v[80:83], v246, s[20:21] offset:256
	global_load_dwordx4 v[84:87], v246, s[20:21] offset:320
	global_load_dwordx4 v[88:91], v247, s[20:21] offset:0
	global_load_dwordx4 v[92:95], v247, s[20:21] offset:64
	global_load_dwordx4 v[96:99], v247, s[20:21] offset:128
	global_load_dwordx4 v[100:103], v247, s[20:21] offset:192
	global_load_dwordx4 v[104:107], v247, s[20:21] offset:256
	global_load_dwordx4 v[108:111], v247, s[20:21] offset:320
	v_and_b32_e32 v248, 3, v244
	v_xor_b32_e32 v248, v248, v245
	v_mul_u32_u24_e32 v249, 0x180, v244
	v_lshl_add_u32 v249, v248, 4, v249
	v_bfe_u32 v248, v244, 2, 1
	v_lshlrev_b32_e32 v248, 6, v248
	v_add_u32_e32 v202, v249, v248
	v_sub_u32_e32 v203, v249, v248
	v_add_u32_e32 v203, 64, v203
	v_add_u32_e32 v204, 0x6000, v202
	v_add_u32_e32 v205, 0x6000, v203
	v_bfe_u32 v248, v235, 4, 1
	v_bfe_u32 v249, v235, 2, 2
	v_lshl_or_b32 v248, v248, 2, v249
	v_lshrrev_b32_e32 v249, 5, v235
	v_lshlrev_b32_e32 v249, 11, v249
	v_and_b32_e32 v250, 3, v235
	v_lshl_or_b32 v249, v250, 3, v249
	v_xor_b32_e32 v250, 0, v248
	v_lshl_add_u32 v206, v250, 5, v249
	v_xor_b32_e32 v250, 1, v248
	v_lshl_add_u32 v207, v250, 5, v249
	v_add_u32_e32 v207, 256, v207
	v_xor_b32_e32 v250, 2, v248
	v_lshl_add_u32 v208, v250, 5, v249
	v_add_u32_e32 v208, 512, v208
	v_xor_b32_e32 v250, 3, v248
	v_lshl_add_u32 v209, v250, 5, v249
	v_add_u32_e32 v209, 768, v209
	v_xor_b32_e32 v250, 4, v248
	v_lshl_add_u32 v210, v250, 5, v249
	v_add_u32_e32 v210, 1024, v210
	v_xor_b32_e32 v250, 5, v248
	v_lshl_add_u32 v211, v250, 5, v249
	v_add_u32_e32 v211, 1280, v211
	v_xor_b32_e32 v250, 6, v248
	v_lshl_add_u32 v212, v250, 5, v249
	v_add_u32_e32 v212, 1536, v212
	v_xor_b32_e32 v250, 7, v248
	v_lshl_add_u32 v213, v250, 5, v249
	v_add_u32_e32 v213, 1792, v213
	v_lshrrev_b32_e32 v248, 4, v195
	v_and_b32_e32 v249, 15, v195
	v_lshlrev_b32_e32 v249, 4, v249
	v_and_b32_e32 v250, 7, v248
	v_lshlrev_b32_e32 v251, 4, v250
	v_xor_b32_e32 v249, v249, v251
	v_mul_u32_u24_e32 v214, 0x180, v248
	v_add_u32_e32 v214, v214, v249
	v_add_u32_e32 v215, 0x3000, v214
	v_bfe_u32 v249, v195, 1, 3
	v_xor_b32_e32 v250, v250, v249
	v_lshrrev_b32_e32 v251, 3, v248
	v_lshl_or_b32 v251, v251, 3, v249
	v_lshlrev_b32_e32 v251, 8, v251
	v_lshl_add_u32 v217, v250, 5, v251
	v_and_b32_e32 v250, 1, v195
	v_lshl_add_u32 v217, v250, 4, v217
	v_lshrrev_b32_e32 v248, 3, v195
	v_and_b32_e32 v249, 7, v195
	v_and_b32_e32 v250, 7, v248
	v_xor_b32_e32 v249, v249, v250
	v_lshlrev_b32_e32 v249, 4, v249
	v_mul_u32_u24_e32 v216, 0x180, v248
	v_add_u32_e32 v216, v216, v249
	v_add_u32_e32 v216, 0x100, v216
	s_lshl_b32 s41, s40, 8
	s_add_u32 s41, s41, 81920
	v_lshl_add_u32 v219, v244, 2, s41
	v_lshl_add_u32 v232, v245, 4, s41
	v_xor_b32_e32 v112, 16, v235
	v_lshlrev_b32_e32 v112, 2, v112
	v_mov_b32_e32 v220, 0
	v_mov_b32_e32 v222, 0
	v_mov_b32_e32 v224, 0
	v_mov_b32_e32 v225, 0
	v_mov_b32_e32 v226, 0
	v_mov_b32_e32 v227, 0
	v_mov_b32_e32 v221, 0
	v_mov_b32_e32 v223, 0
	v_mov_b32_e32 v228, 0
	v_mov_b32_e32 v229, 0
	v_mov_b32_e32 v230, 0
	v_mov_b32_e32 v231, 0
	v_mov_b32_e32 v0, 0
	v_mov_b32_e32 v1, 0
	v_mov_b32_e32 v2, 0
	v_mov_b32_e32 v3, 0
	v_mov_b32_e32 v4, 0
	v_mov_b32_e32 v5, 0
	v_mov_b32_e32 v6, 0
	v_mov_b32_e32 v7, 0
	v_mov_b32_e32 v8, 0
	v_mov_b32_e32 v9, 0
	v_mov_b32_e32 v10, 0
	v_mov_b32_e32 v11, 0
	v_mov_b32_e32 v12, 0
	v_mov_b32_e32 v13, 0
	v_mov_b32_e32 v14, 0
	v_mov_b32_e32 v15, 0
	v_mov_b32_e32 v16, 0
	v_mov_b32_e32 v17, 0
	v_mov_b32_e32 v18, 0
	v_mov_b32_e32 v19, 0
	v_mov_b32_e32 v20, 0
	v_mov_b32_e32 v21, 0
	v_mov_b32_e32 v22, 0
	v_mov_b32_e32 v23, 0
	v_mov_b32_e32 v24, 0
	v_mov_b32_e32 v25, 0
	v_mov_b32_e32 v26, 0
	v_mov_b32_e32 v27, 0
	v_mov_b32_e32 v28, 0
	v_mov_b32_e32 v29, 0
	v_mov_b32_e32 v30, 0
	v_mov_b32_e32 v31, 0
	v_mov_b32_e32 v32, 0
	v_mov_b32_e32 v33, 0
	v_mov_b32_e32 v34, 0
	v_mov_b32_e32 v35, 0
	v_mov_b32_e32 v36, 0
	v_mov_b32_e32 v37, 0
	v_mov_b32_e32 v38, 0
	v_mov_b32_e32 v39, 0
	v_mov_b32_e32 v40, 0
	v_mov_b32_e32 v41, 0
	v_mov_b32_e32 v42, 0
	v_mov_b32_e32 v43, 0
	v_mov_b32_e32 v44, 0
	v_mov_b32_e32 v45, 0
	v_mov_b32_e32 v46, 0
	v_mov_b32_e32 v47, 0
	v_mov_b32_e32 v48, 0
	v_mov_b32_e32 v49, 0
	v_mov_b32_e32 v50, 0
	v_mov_b32_e32 v51, 0
	v_mov_b32_e32 v52, 0
	v_mov_b32_e32 v53, 0
	v_mov_b32_e32 v54, 0
	v_mov_b32_e32 v55, 0
	v_mov_b32_e32 v56, 0
	v_mov_b32_e32 v57, 0
	v_mov_b32_e32 v58, 0
	v_mov_b32_e32 v59, 0
	v_mov_b32_e32 v60, 0
	v_mov_b32_e32 v61, 0
	v_mov_b32_e32 v62, 0
	v_mov_b32_e32 v63, 0
	s_waitcnt vmcnt(12)
; __device__ __forceinline__ void qkt(f32x16& p0, f32x16& p1, const char* Ks, const bf16x8* qr, const char* qL, int r32, int hi, float negm) {
; #pragma unroll
;   for (int r = 0; r < 16; ++r) { p0[r] = negm; p1[r] = negm; }
; #pragma unroll
;   for (int d0 = 0; d0 < 12; ++d0) { int cb = (d0 * 16 + hi * 8) * 2;
;     bf16x8 b0 = *reinterpret_cast<const bf16x8*>(Ks + KSWZ(r32, cb));
;     bf16x8 b1 = *reinterpret_cast<const bf16x8*>(Ks + KSWZ(32 + r32, cb));
;     const bf16x8 q = d0 < 8 ? qr[d0 < 8 ? d0 : 0] : *reinterpret_cast<const bf16x8*>(qL + (d0 - 8) * 1024);
;     p0 = __builtin_amdgcn_mfma_f32_32x32x16_bf16(b0, q, p0, 0, 0, 0);
;     p1 = __builtin_amdgcn_mfma_f32_32x32x16_bf16(b1, q, p1, 0, 0, 0); }
; }
	ds_write_b128 v214, v[178:181] offset:32768
	ds_write_b128 v215, v[182:185] offset:32768
	ds_write_b128 v216, v[196:199] offset:32768
	ds_write_b128 v217, v[186:189] offset:0
	ds_write_b128 v217, v[190:193] offset:8192
	global_load_dwordx4 v[178:181], v218, s[22:23]
	global_load_dwordx4 v[182:185], v218, s[24:25]
	global_load_dwordx4 v[196:199], v218, s[34:35]
	global_load_dwordx4 v[186:189], v218, s[26:27]
	global_load_dwordx4 v[190:193], v218, s[30:31]
	s_add_u32 s22, s22, 16384
	s_addc_u32 s23, s23, 0
	s_add_u32 s24, s24, 16384
	s_addc_u32 s25, s25, 0
	s_add_u32 s26, s26, 16384
	s_addc_u32 s27, s27, 0
	s_add_u32 s30, s30, 16384
	s_addc_u32 s31, s31, 0
	s_add_u32 s34, s34, 8192
	s_addc_u32 s35, s35, 0
	s_waitcnt vmcnt(5)
	s_waitcnt lgkmcnt(0)
	s_barrier
	ds_read_b128 v[162:165], v202 offset:32768
	ds_read_b128 v[166:169], v202 offset:38912
	ds_read_b128 v[170:173], v202 offset:45056
	s_waitcnt lgkmcnt(2)
	v_mfma_f32_16x16x32_bf16 v[114:117], v[162:165], v[64:67], v[224:227]
	v_mfma_f32_16x16x32_bf16 v[118:121], v[162:165], v[88:91], v[228:231]
	ds_read_b128 v[174:177], v202 offset:51200
	s_waitcnt lgkmcnt(2)
	v_mfma_f32_16x16x32_bf16 v[126:129], v[166:169], v[88:91], v[228:231]
	v_mfma_f32_16x16x32_bf16 v[122:125], v[166:169], v[64:67], v[224:227]
	ds_read_b128 v[162:165], v203 offset:32768
	s_waitcnt lgkmcnt(2)
	v_mfma_f32_16x16x32_bf16 v[130:133], v[170:173], v[64:67], v[224:227]
	v_mfma_f32_16x16x32_bf16 v[134:137], v[170:173], v[88:91], v[228:231]
	ds_read_b128 v[166:169], v203 offset:38912
	s_waitcnt lgkmcnt(2)
	v_mfma_f32_16x16x32_bf16 v[142:145], v[174:177], v[88:91], v[228:231]
	v_mfma_f32_16x16x32_bf16 v[138:141], v[174:177], v[64:67], v[224:227]
	ds_read_b128 v[170:173], v203 offset:45056
	s_waitcnt lgkmcnt(2)
	v_mfma_f32_16x16x32_bf16 v[114:117], v[162:165], v[68:71], v[114:117]
	v_mfma_f32_16x16x32_bf16 v[118:121], v[162:165], v[92:95], v[118:121]
	ds_read_b128 v[174:177], v203 offset:51200
	s_waitcnt lgkmcnt(2)
	v_mfma_f32_16x16x32_bf16 v[126:129], v[166:169], v[92:95], v[126:129]
	v_mfma_f32_16x16x32_bf16 v[122:125], v[166:169], v[68:71], v[122:125]
	ds_read_b128 v[162:165], v202 offset:32896
	s_waitcnt lgkmcnt(2)
	v_mfma_f32_16x16x32_bf16 v[130:133], v[170:173], v[68:71], v[130:133]
	v_mfma_f32_16x16x32_bf16 v[134:137], v[170:173], v[92:95], v[134:137]
	ds_read_b128 v[166:169], v202 offset:39040
	s_waitcnt lgkmcnt(2)
	v_mfma_f32_16x16x32_bf16 v[142:145], v[174:177], v[92:95], v[142:145]
	v_mfma_f32_16x16x32_bf16 v[138:141], v[174:177], v[68:71], v[138:141]
	ds_read_b128 v[170:173], v202 offset:45184
	s_waitcnt lgkmcnt(2)
	v_mfma_f32_16x16x32_bf16 v[114:117], v[162:165], v[72:75], v[114:117]
	v_mfma_f32_16x16x32_bf16 v[118:121], v[162:165], v[96:99], v[118:121]
	ds_read_b128 v[174:177], v202 offset:51328
	s_waitcnt lgkmcnt(2)
	v_mfma_f32_16x16x32_bf16 v[126:129], v[166:169], v[96:99], v[126:129]
	v_mfma_f32_16x16x32_bf16 v[122:125], v[166:169], v[72:75], v[122:125]
	ds_read_b128 v[162:165], v203 offset:32896
	s_waitcnt lgkmcnt(2)
	v_mfma_f32_16x16x32_bf16 v[130:133], v[170:173], v[72:75], v[130:133]
	v_mfma_f32_16x16x32_bf16 v[134:137], v[170:173], v[96:99], v[134:137]
	ds_read_b128 v[166:169], v203 offset:39040
	s_waitcnt lgkmcnt(2)
	v_mfma_f32_16x16x32_bf16 v[142:145], v[174:177], v[96:99], v[142:145]
	v_mfma_f32_16x16x32_bf16 v[138:141], v[174:177], v[72:75], v[138:141]
	ds_read_b128 v[170:173], v203 offset:45184
	s_waitcnt lgkmcnt(2)
	v_mfma_f32_16x16x32_bf16 v[114:117], v[162:165], v[76:79], v[114:117]
	v_mfma_f32_16x16x32_bf16 v[118:121], v[162:165], v[100:103], v[118:121]
	ds_read_b128 v[174:177], v203 offset:51328
	s_waitcnt lgkmcnt(2)
	v_mfma_f32_16x16x32_bf16 v[126:129], v[166:169], v[100:103], v[126:129]
	v_mfma_f32_16x16x32_bf16 v[122:125], v[166:169], v[76:79], v[122:125]
	ds_read_b128 v[162:165], v202 offset:33024
	s_waitcnt lgkmcnt(2)
	v_mfma_f32_16x16x32_bf16 v[130:133], v[170:173], v[76:79], v[130:133]
	v_mfma_f32_16x16x32_bf16 v[134:137], v[170:173], v[100:103], v[134:137]
	ds_read_b128 v[166:169], v202 offset:39168
	s_waitcnt lgkmcnt(2)
	v_mfma_f32_16x16x32_bf16 v[142:145], v[174:177], v[100:103], v[142:145]
	v_mfma_f32_16x16x32_bf16 v[138:141], v[174:177], v[76:79], v[138:141]
	ds_read_b128 v[170:173], v202 offset:45312
	s_waitcnt lgkmcnt(2)
	v_mfma_f32_16x16x32_bf16 v[114:117], v[162:165], v[80:83], v[114:117]
	v_mfma_f32_16x16x32_bf16 v[118:121], v[162:165], v[104:107], v[118:121]
	ds_read_b128 v[174:177], v202 offset:51456
	s_waitcnt lgkmcnt(2)
	v_mfma_f32_16x16x32_bf16 v[126:129], v[166:169], v[104:107], v[126:129]
	v_mfma_f32_16x16x32_bf16 v[122:125], v[166:169], v[80:83], v[122:125]
	ds_read_b128 v[162:165], v203 offset:33024
	s_waitcnt lgkmcnt(2)
	v_mfma_f32_16x16x32_bf16 v[130:133], v[170:173], v[80:83], v[130:133]
	v_mfma_f32_16x16x32_bf16 v[134:137], v[170:173], v[104:107], v[134:137]
	ds_read_b128 v[166:169], v203 offset:39168
	s_waitcnt lgkmcnt(2)
	v_mfma_f32_16x16x32_bf16 v[142:145], v[174:177], v[104:107], v[142:145]
	v_mfma_f32_16x16x32_bf16 v[138:141], v[174:177], v[80:83], v[138:141]
	ds_read_b128 v[170:173], v203 offset:45312
	s_waitcnt lgkmcnt(2)
	v_mfma_f32_16x16x32_bf16 v[114:117], v[162:165], v[84:87], v[114:117]
	v_mfma_f32_16x16x32_bf16 v[118:121], v[162:165], v[108:111], v[118:121]
	ds_read_b128 v[174:177], v203 offset:51456
	s_waitcnt lgkmcnt(2)
	v_mfma_f32_16x16x32_bf16 v[126:129], v[166:169], v[108:111], v[126:129]
	v_mfma_f32_16x16x32_bf16 v[122:125], v[166:169], v[84:87], v[122:125]
	s_waitcnt lgkmcnt(1)
	v_mfma_f32_16x16x32_bf16 v[130:133], v[170:173], v[84:87], v[130:133]
	v_mfma_f32_16x16x32_bf16 v[134:137], v[170:173], v[108:111], v[134:137]
	s_waitcnt lgkmcnt(0)
	v_mfma_f32_16x16x32_bf16 v[142:145], v[174:177], v[108:111], v[142:145]
	v_mfma_f32_16x16x32_bf16 v[138:141], v[174:177], v[84:87], v[138:141]
	ds_read_b64_tr_b16 v[162:163], v206 offset:0
	ds_read_b64_tr_b16 v[164:165], v206 offset:4096
	ds_read_b64_tr_b16 v[166:167], v207 offset:0
	ds_read_b64_tr_b16 v[168:169], v207 offset:4096
	ds_read_b64_tr_b16 v[170:171], v208 offset:0
	ds_read_b64_tr_b16 v[172:173], v208 offset:4096
	s_nop 7
	v_max3_f32 v233, v114, v115, v116
	v_max_f32_e32 v233, v233, v117
	v_max3_f32 v234, v118, v119, v120
	v_max_f32_e32 v234, v234, v121
	v_max3_f32 v233, v233, v122, v123
	v_max3_f32 v233, v233, v124, v125
	v_max3_f32 v234, v234, v126, v127
	v_max3_f32 v234, v234, v128, v129
	v_max3_f32 v233, v233, v130, v131
	v_max3_f32 v233, v233, v132, v133
	v_max3_f32 v234, v234, v134, v135
	v_max3_f32 v234, v234, v136, v137
	v_max3_f32 v233, v233, v138, v139
	v_max3_f32 v233, v233, v140, v141
	v_max3_f32 v234, v234, v142, v143
	v_max3_f32 v234, v234, v144, v145
	s_branch .Lat_rare_0
; __device__ __forceinline__ void finishSM(f32x16& p0, f32x16& p1, float alpha, float& l_reg, bf16x8& pa0, bf16x8& pa1, bf16x8& pa2, bf16x8& pa3) {
; #pragma unroll
;   for (int r = 0; r < 16; ++r) p1[r] = __builtin_amdgcn_exp2f(p1[r]);
;   float ps = 0;
; #pragma unroll
;   for (int r = 0; r < 16; ++r) ps += p0[r];
; #pragma unroll
;   for (int r = 0; r < 16; ++r) ps += p1[r];
;   { auto rr = __builtin_amdgcn_permlane32_swap(__float_as_uint(ps), __float_as_uint(ps), false, false);
;     ps = __uint_as_float(rr[0]) + __uint_as_float(rr[1]); }
;   l_reg = l_reg * alpha + ps;
;     ...
;   PK4(p0, 0, pa0); PK4(p0, 8, pa1); PK4(p1, 0, pa2); PK4(p1, 8, pa3);
;     ...
; }
; __device__ __forceinline__ void qkt(f32x16& p0, f32x16& p1, const char* Ks, const bf16x8* qr, const char* qL, int r32, int hi, float negm) {
; #pragma unroll
;   for (int r = 0; r < 16; ++r) { p0[r] = negm; p1[r] = negm; }
; #pragma unroll
;   for (int d0 = 0; d0 < 12; ++d0) { int cb = (d0 * 16 + hi * 8) * 2;
;     bf16x8 b0 = *reinterpret_cast<const bf16x8*>(Ks + KSWZ(r32, cb));
;     bf16x8 b1 = *reinterpret_cast<const bf16x8*>(Ks + KSWZ(32 + r32, cb));
;     const bf16x8 q = d0 < 8 ? qr[d0 < 8 ? d0 : 0] : *reinterpret_cast<const bf16x8*>(qL + (d0 - 8) * 1024);
;     p0 = __builtin_amdgcn_mfma_f32_32x32x16_bf16(b0, q, p0, 0, 0, 0);
;     p1 = __builtin_amdgcn_mfma_f32_32x32x16_bf16(b1, q, p1, 0, 0, 0); }
; }
; __device__ __forceinline__ int v_st(int k, int c) { const int kk = (k & ~0xC) | ((k & 4) << 1) | ((k & 8) >> 1); return ((kk >> 3) * 4 + (c >> 5)) * 512 + ((kk & 7) * 32 + (c & 31)) * 2; }
; __device__ __forceinline__ int v_rd_base(int lane) { return ((lane & 3) << 3) | (((lane >> 2) & 3) << 6) | (((lane >> 4) & 1) << 5) | (((lane >> 5) & 1) << 8); }
; template <int OFF> __device__ __forceinline__ s16x4 tr_read(int vb) {
;   s16x4 r; asm volatile("ds_read_b64_tr_b16 %0, %1 offset:%2" : "=&v"(r) : "v"(vb), "i"(OFF) : "memory"); return r;
; }
; template <int D0> __device__ __forceinline__ void pv_one(f32x16& od, int vb, bf16x8 pa0, bf16x8 pa1, bf16x8 pa2, bf16x8 pa3) {
;   const s16x4 l0 = tr_read<v_rd_off(D0, 0, 0)>(vb), h0 = tr_read<v_rd_off(D0, 0, 1)>(vb), l1 = tr_read<v_rd_off(D0, 1, 0)>(vb), h1 = tr_read<v_rd_off(D0, 1, 1)>(vb);
;   const s16x4 l2 = tr_read<v_rd_off(D0, 2, 0)>(vb), h2 = tr_read<v_rd_off(D0, 2, 1)>(vb), l3 = tr_read<v_rd_off(D0, 3, 0)>(vb), h3 = tr_read<v_rd_off(D0, 3, 1)>(vb);
.Lat_cont_0:
	v_exp_f32_e32 v114, v114
	v_exp_f32_e32 v115, v115
	v_exp_f32_e32 v116, v116
	v_exp_f32_e32 v117, v117
	v_add_f32_e32 v222, v222, v114
	v_add_f32_e32 v222, v222, v115
	v_add_f32_e32 v222, v222, v116
	v_add_f32_e32 v222, v222, v117
	v_exp_f32_e32 v122, v122
	v_exp_f32_e32 v123, v123
	v_exp_f32_e32 v124, v124
	v_exp_f32_e32 v125, v125
	v_add_f32_e32 v222, v222, v122
	v_add_f32_e32 v222, v222, v123
	v_add_f32_e32 v222, v222, v124
	v_add_f32_e32 v222, v222, v125
	v_cvt_pk_bf16_f32 v146, v114, v115
	v_cvt_pk_bf16_f32 v147, v116, v117
	v_cvt_pk_bf16_f32 v148, v122, v123
	v_cvt_pk_bf16_f32 v149, v124, v125
	v_exp_f32_e32 v118, v118
	v_exp_f32_e32 v119, v119
	v_exp_f32_e32 v120, v120
	v_exp_f32_e32 v121, v121
	v_add_f32_e32 v223, v223, v118
	v_add_f32_e32 v223, v223, v119
	v_add_f32_e32 v223, v223, v120
	v_add_f32_e32 v223, v223, v121
	v_exp_f32_e32 v126, v126
	v_exp_f32_e32 v127, v127
	v_exp_f32_e32 v128, v128
	v_exp_f32_e32 v129, v129
	v_add_f32_e32 v223, v223, v126
	v_add_f32_e32 v223, v223, v127
	v_add_f32_e32 v223, v223, v128
	v_add_f32_e32 v223, v223, v129
	v_cvt_pk_bf16_f32 v154, v118, v119
	v_cvt_pk_bf16_f32 v155, v120, v121
	v_cvt_pk_bf16_f32 v156, v126, v127
	v_cvt_pk_bf16_f32 v157, v128, v129
	s_nop 1
	s_waitcnt lgkmcnt(4)
	v_mfma_f32_16x16x32_bf16 v[0:3], v[146:149], v[162:165], v[0:3]
	v_mfma_f32_16x16x32_bf16 v[32:35], v[154:157], v[162:165], v[32:35]
	ds_read_b64_tr_b16 v[174:175], v209 offset:0
	ds_read_b64_tr_b16 v[176:177], v209 offset:4096
	v_exp_f32_e32 v130, v130
	v_exp_f32_e32 v131, v131
	v_exp_f32_e32 v132, v132
	v_exp_f32_e32 v133, v133
	v_add_f32_e32 v222, v222, v130
	s_waitcnt lgkmcnt(4)
	v_mfma_f32_16x16x32_bf16 v[36:39], v[154:157], v[166:169], v[36:39]
	v_mfma_f32_16x16x32_bf16 v[4:7], v[146:149], v[166:169], v[4:7]
	ds_read_b64_tr_b16 v[162:163], v210 offset:0
	ds_read_b64_tr_b16 v[164:165], v210 offset:4096
	v_add_f32_e32 v222, v222, v131
	v_add_f32_e32 v222, v222, v132
	v_add_f32_e32 v222, v222, v133
	v_exp_f32_e32 v138, v138
	v_exp_f32_e32 v139, v139
	s_waitcnt lgkmcnt(4)
	v_mfma_f32_16x16x32_bf16 v[8:11], v[146:149], v[170:173], v[8:11]
	v_mfma_f32_16x16x32_bf16 v[40:43], v[154:157], v[170:173], v[40:43]
	ds_read_b64_tr_b16 v[166:167], v211 offset:0
	ds_read_b64_tr_b16 v[168:169], v211 offset:4096
	v_exp_f32_e32 v140, v140
	v_exp_f32_e32 v141, v141
	v_add_f32_e32 v222, v222, v138
	v_add_f32_e32 v222, v222, v139
	v_add_f32_e32 v222, v222, v140
	s_waitcnt lgkmcnt(4)
	v_mfma_f32_16x16x32_bf16 v[44:47], v[154:157], v[174:177], v[44:47]
	v_mfma_f32_16x16x32_bf16 v[12:15], v[146:149], v[174:177], v[12:15]
	ds_read_b64_tr_b16 v[170:171], v212 offset:0
	ds_read_b64_tr_b16 v[172:173], v212 offset:4096
	v_add_f32_e32 v222, v222, v141
	v_cvt_pk_bf16_f32 v150, v130, v131
	v_cvt_pk_bf16_f32 v151, v132, v133
	v_cvt_pk_bf16_f32 v152, v138, v139
	v_cvt_pk_bf16_f32 v153, v140, v141
	s_waitcnt lgkmcnt(4)
	v_mfma_f32_16x16x32_bf16 v[16:19], v[146:149], v[162:165], v[16:19]
	v_mfma_f32_16x16x32_bf16 v[48:51], v[154:157], v[162:165], v[48:51]
	ds_read_b64_tr_b16 v[174:175], v213 offset:0
	ds_read_b64_tr_b16 v[176:177], v213 offset:4096
	v_exp_f32_e32 v134, v134
	v_exp_f32_e32 v135, v135
	v_exp_f32_e32 v136, v136
	v_exp_f32_e32 v137, v137
	v_add_f32_e32 v223, v223, v134
	s_waitcnt lgkmcnt(4)
	v_mfma_f32_16x16x32_bf16 v[52:55], v[154:157], v[166:169], v[52:55]
	v_mfma_f32_16x16x32_bf16 v[20:23], v[146:149], v[166:169], v[20:23]
	ds_read_b64_tr_b16 v[162:163], v206 offset:8192
	ds_read_b64_tr_b16 v[164:165], v206 offset:12288
	v_add_f32_e32 v223, v223, v135
	v_add_f32_e32 v223, v223, v136
	v_add_f32_e32 v223, v223, v137
	v_exp_f32_e32 v142, v142
	v_exp_f32_e32 v143, v143
	s_waitcnt lgkmcnt(4)
	v_mfma_f32_16x16x32_bf16 v[24:27], v[146:149], v[170:173], v[24:27]
	v_mfma_f32_16x16x32_bf16 v[56:59], v[154:157], v[170:173], v[56:59]
	ds_read_b64_tr_b16 v[166:167], v207 offset:8192
	ds_read_b64_tr_b16 v[168:169], v207 offset:12288
	v_exp_f32_e32 v144, v144
	v_exp_f32_e32 v145, v145
	v_add_f32_e32 v223, v223, v142
	v_add_f32_e32 v223, v223, v143
	v_add_f32_e32 v223, v223, v144
	s_waitcnt lgkmcnt(4)
	v_mfma_f32_16x16x32_bf16 v[60:63], v[154:157], v[174:177], v[60:63]
	v_mfma_f32_16x16x32_bf16 v[28:31], v[146:149], v[174:177], v[28:31]
	ds_read_b64_tr_b16 v[170:171], v208 offset:8192
	ds_read_b64_tr_b16 v[172:173], v208 offset:12288
	v_add_f32_e32 v223, v223, v145
	v_cvt_pk_bf16_f32 v158, v134, v135
	v_cvt_pk_bf16_f32 v159, v136, v137
	v_cvt_pk_bf16_f32 v160, v142, v143
	v_cvt_pk_bf16_f32 v161, v144, v145
	s_waitcnt lgkmcnt(4)
	s_nop 1
	v_mfma_f32_16x16x32_bf16 v[0:3], v[150:153], v[162:165], v[0:3]
	v_mfma_f32_16x16x32_bf16 v[32:35], v[158:161], v[162:165], v[32:35]
	ds_read_b64_tr_b16 v[174:175], v209 offset:8192
	ds_read_b64_tr_b16 v[176:177], v209 offset:12288
	s_waitcnt lgkmcnt(4)
	v_mfma_f32_16x16x32_bf16 v[36:39], v[158:161], v[166:169], v[36:39]
	v_mfma_f32_16x16x32_bf16 v[4:7], v[150:153], v[166:169], v[4:7]
	ds_read_b64_tr_b16 v[162:163], v210 offset:8192
	ds_read_b64_tr_b16 v[164:165], v210 offset:12288
	s_waitcnt lgkmcnt(4)
	v_mfma_f32_16x16x32_bf16 v[8:11], v[150:153], v[170:173], v[8:11]
	v_mfma_f32_16x16x32_bf16 v[40:43], v[158:161], v[170:173], v[40:43]
	ds_read_b64_tr_b16 v[166:167], v211 offset:8192
	ds_read_b64_tr_b16 v[168:169], v211 offset:12288
	s_waitcnt lgkmcnt(4)
	v_mfma_f32_16x16x32_bf16 v[44:47], v[158:161], v[174:177], v[44:47]
	v_mfma_f32_16x16x32_bf16 v[12:15], v[150:153], v[174:177], v[12:15]
	ds_read_b64_tr_b16 v[170:171], v212 offset:8192
	ds_read_b64_tr_b16 v[172:173], v212 offset:12288
	s_waitcnt lgkmcnt(4)
	v_mfma_f32_16x16x32_bf16 v[16:19], v[150:153], v[162:165], v[16:19]
	v_mfma_f32_16x16x32_bf16 v[48:51], v[158:161], v[162:165], v[48:51]
	ds_read_b64_tr_b16 v[174:175], v213 offset:8192
	ds_read_b64_tr_b16 v[176:177], v213 offset:12288
	s_waitcnt lgkmcnt(4)
	v_mfma_f32_16x16x32_bf16 v[52:55], v[158:161], v[166:169], v[52:55]
	v_mfma_f32_16x16x32_bf16 v[20:23], v[150:153], v[166:169], v[20:23]
	s_waitcnt vmcnt(0)
	ds_write_b128 v214, v[178:181] offset:57344
	ds_write_b128 v215, v[182:185] offset:57344
	ds_write_b128 v216, v[196:199] offset:57344
	ds_write_b128 v217, v[186:189] offset:16384
	ds_write_b128 v217, v[190:193] offset:24576
	global_load_dwordx4 v[178:181], v218, s[22:23]
	global_load_dwordx4 v[182:185], v218, s[24:25]
	global_load_dwordx4 v[196:199], v218, s[34:35]
	global_load_dwordx4 v[186:189], v218, s[26:27]
	global_load_dwordx4 v[190:193], v218, s[30:31]
	s_add_u32 s22, s22, 16384
	s_addc_u32 s23, s23, 0
	s_add_u32 s24, s24, 16384
	s_addc_u32 s25, s25, 0
	s_add_u32 s26, s26, 16384
	s_addc_u32 s27, s27, 0
	s_add_u32 s30, s30, 16384
	s_addc_u32 s31, s31, 0
	s_add_u32 s34, s34, 8192
	s_addc_u32 s35, s35, 0
	s_waitcnt lgkmcnt(7)
	v_mfma_f32_16x16x32_bf16 v[24:27], v[150:153], v[170:173], v[24:27]
	v_mfma_f32_16x16x32_bf16 v[56:59], v[158:161], v[170:173], v[56:59]
	s_waitcnt lgkmcnt(5)
	v_mfma_f32_16x16x32_bf16 v[60:63], v[158:161], v[174:177], v[60:63]
	v_mfma_f32_16x16x32_bf16 v[28:31], v[150:153], v[174:177], v[28:31]
	s_waitcnt lgkmcnt(0)
	s_barrier
; template <bool FIRST>
; __device__ __forceinline__ void partialSM(f32x16& p0, f32x16& p1, float& m_reg, float& alpha) {
;   constexpr float THR2 = THR * 1.4426950408889634f;
;   float pmax = p0[0];
; #pragma unroll
;   for (int r = 1; r < 16; ++r) pmax = fmaxf(pmax, p0[r]);
; #pragma unroll
;   for (int r = 0; r < 16; ++r) pmax = fmaxf(pmax, p1[r]);
;   { auto rr = __builtin_amdgcn_permlane32_swap(__float_as_uint(pmax), __float_as_uint(pmax), false, false);
;     pmax = fmaxf(__uint_as_float(rr[0]), __uint_as_float(rr[1])); }
;   if (!FIRST && __builtin_expect(__all(pmax <= THR2), 1)) { alpha = 1.f; }
; __device__ __forceinline__ void qkt(f32x16& p0, f32x16& p1, const char* Ks, const bf16x8* qr, const char* qL, int r32, int hi, float negm) {
; #pragma unroll
;   for (int r = 0; r < 16; ++r) { p0[r] = negm; p1[r] = negm; }
; #pragma unroll
;   for (int d0 = 0; d0 < 12; ++d0) { int cb = (d0 * 16 + hi * 8) * 2;
;     bf16x8 b0 = *reinterpret_cast<const bf16x8*>(Ks + KSWZ(r32, cb));
;     bf16x8 b1 = *reinterpret_cast<const bf16x8*>(Ks + KSWZ(32 + r32, cb));
;     const bf16x8 q = d0 < 8 ? qr[d0 < 8 ? d0 : 0] : *reinterpret_cast<const bf16x8*>(qL + (d0 - 8) * 1024);
;     p0 = __builtin_amdgcn_mfma_f32_32x32x16_bf16(b0, q, p0, 0, 0, 0);
;     p1 = __builtin_amdgcn_mfma_f32_32x32x16_bf16(b1, q, p1, 0, 0, 0); }
; }
	s_movk_i32 s39, 127
.Lat_loop:
	ds_read_b128 v[162:165], v204 offset:32768
	ds_read_b128 v[166:169], v204 offset:38912
	ds_read_b128 v[170:173], v204 offset:45056
	s_waitcnt lgkmcnt(2)
	v_mfma_f32_16x16x32_bf16 v[114:117], v[162:165], v[64:67], v[224:227]
	v_mfma_f32_16x16x32_bf16 v[118:121], v[162:165], v[88:91], v[228:231]
	ds_read_b128 v[174:177], v204 offset:51200
	s_waitcnt lgkmcnt(2)
	v_mfma_f32_16x16x32_bf16 v[126:129], v[166:169], v[88:91], v[228:231]
	v_mfma_f32_16x16x32_bf16 v[122:125], v[166:169], v[64:67], v[224:227]
	ds_read_b128 v[162:165], v205 offset:32768
	s_waitcnt lgkmcnt(2)
	v_mfma_f32_16x16x32_bf16 v[130:133], v[170:173], v[64:67], v[224:227]
	v_mfma_f32_16x16x32_bf16 v[134:137], v[170:173], v[88:91], v[228:231]
	ds_read_b128 v[166:169], v205 offset:38912
	s_waitcnt lgkmcnt(2)
	v_mfma_f32_16x16x32_bf16 v[142:145], v[174:177], v[88:91], v[228:231]
	v_mfma_f32_16x16x32_bf16 v[138:141], v[174:177], v[64:67], v[224:227]
	ds_read_b128 v[170:173], v205 offset:45056
	s_waitcnt lgkmcnt(2)
	v_mfma_f32_16x16x32_bf16 v[114:117], v[162:165], v[68:71], v[114:117]
	v_mfma_f32_16x16x32_bf16 v[118:121], v[162:165], v[92:95], v[118:121]
	ds_read_b128 v[174:177], v205 offset:51200
	s_waitcnt lgkmcnt(2)
	v_mfma_f32_16x16x32_bf16 v[126:129], v[166:169], v[92:95], v[126:129]
	v_mfma_f32_16x16x32_bf16 v[122:125], v[166:169], v[68:71], v[122:125]
	ds_read_b128 v[162:165], v204 offset:32896
	s_waitcnt lgkmcnt(2)
	v_mfma_f32_16x16x32_bf16 v[130:133], v[170:173], v[68:71], v[130:133]
	v_mfma_f32_16x16x32_bf16 v[134:137], v[170:173], v[92:95], v[134:137]
	ds_read_b128 v[166:169], v204 offset:39040
	s_waitcnt lgkmcnt(2)
	v_mfma_f32_16x16x32_bf16 v[142:145], v[174:177], v[92:95], v[142:145]
	v_mfma_f32_16x16x32_bf16 v[138:141], v[174:177], v[68:71], v[138:141]
	ds_read_b128 v[170:173], v204 offset:45184
	s_waitcnt lgkmcnt(2)
	v_mfma_f32_16x16x32_bf16 v[114:117], v[162:165], v[72:75], v[114:117]
	v_mfma_f32_16x16x32_bf16 v[118:121], v[162:165], v[96:99], v[118:121]
	ds_read_b128 v[174:177], v204 offset:51328
	s_waitcnt lgkmcnt(2)
	v_mfma_f32_16x16x32_bf16 v[126:129], v[166:169], v[96:99], v[126:129]
	v_mfma_f32_16x16x32_bf16 v[122:125], v[166:169], v[72:75], v[122:125]
	ds_read_b128 v[162:165], v205 offset:32896
	s_waitcnt lgkmcnt(2)
	v_mfma_f32_16x16x32_bf16 v[130:133], v[170:173], v[72:75], v[130:133]
	v_mfma_f32_16x16x32_bf16 v[134:137], v[170:173], v[96:99], v[134:137]
	ds_read_b128 v[166:169], v205 offset:39040
	s_waitcnt lgkmcnt(2)
	v_mfma_f32_16x16x32_bf16 v[142:145], v[174:177], v[96:99], v[142:145]
	v_mfma_f32_16x16x32_bf16 v[138:141], v[174:177], v[72:75], v[138:141]
	ds_read_b128 v[170:173], v205 offset:45184
	s_waitcnt lgkmcnt(2)
	v_mfma_f32_16x16x32_bf16 v[114:117], v[162:165], v[76:79], v[114:117]
	v_mfma_f32_16x16x32_bf16 v[118:121], v[162:165], v[100:103], v[118:121]
	ds_read_b128 v[174:177], v205 offset:51328
	s_waitcnt lgkmcnt(2)
	v_mfma_f32_16x16x32_bf16 v[126:129], v[166:169], v[100:103], v[126:129]
	v_mfma_f32_16x16x32_bf16 v[122:125], v[166:169], v[76:79], v[122:125]
	ds_read_b128 v[162:165], v204 offset:33024
	s_waitcnt lgkmcnt(2)
	v_mfma_f32_16x16x32_bf16 v[130:133], v[170:173], v[76:79], v[130:133]
	v_mfma_f32_16x16x32_bf16 v[134:137], v[170:173], v[100:103], v[134:137]
	ds_read_b128 v[166:169], v204 offset:39168
	s_waitcnt lgkmcnt(2)
	v_mfma_f32_16x16x32_bf16 v[142:145], v[174:177], v[100:103], v[142:145]
	v_mfma_f32_16x16x32_bf16 v[138:141], v[174:177], v[76:79], v[138:141]
	ds_read_b128 v[170:173], v204 offset:45312
	s_waitcnt lgkmcnt(2)
	v_mfma_f32_16x16x32_bf16 v[114:117], v[162:165], v[80:83], v[114:117]
	v_mfma_f32_16x16x32_bf16 v[118:121], v[162:165], v[104:107], v[118:121]
	ds_read_b128 v[174:177], v204 offset:51456
	s_waitcnt lgkmcnt(2)
	v_mfma_f32_16x16x32_bf16 v[126:129], v[166:169], v[104:107], v[126:129]
	v_mfma_f32_16x16x32_bf16 v[122:125], v[166:169], v[80:83], v[122:125]
	ds_read_b128 v[162:165], v205 offset:33024
	s_waitcnt lgkmcnt(2)
	v_mfma_f32_16x16x32_bf16 v[130:133], v[170:173], v[80:83], v[130:133]
	v_mfma_f32_16x16x32_bf16 v[134:137], v[170:173], v[104:107], v[134:137]
	ds_read_b128 v[166:169], v205 offset:39168
	s_waitcnt lgkmcnt(2)
	v_mfma_f32_16x16x32_bf16 v[142:145], v[174:177], v[104:107], v[142:145]
	v_mfma_f32_16x16x32_bf16 v[138:141], v[174:177], v[80:83], v[138:141]
	ds_read_b128 v[170:173], v205 offset:45312
	s_waitcnt lgkmcnt(2)
	v_mfma_f32_16x16x32_bf16 v[114:117], v[162:165], v[84:87], v[114:117]
	v_mfma_f32_16x16x32_bf16 v[118:121], v[162:165], v[108:111], v[118:121]
	ds_read_b128 v[174:177], v205 offset:51456
	s_waitcnt lgkmcnt(2)
	v_mfma_f32_16x16x32_bf16 v[126:129], v[166:169], v[108:111], v[126:129]
	v_mfma_f32_16x16x32_bf16 v[122:125], v[166:169], v[84:87], v[122:125]
	s_waitcnt lgkmcnt(1)
	v_mfma_f32_16x16x32_bf16 v[130:133], v[170:173], v[84:87], v[130:133]
	v_mfma_f32_16x16x32_bf16 v[134:137], v[170:173], v[108:111], v[134:137]
	s_waitcnt lgkmcnt(0)
	v_mfma_f32_16x16x32_bf16 v[142:145], v[174:177], v[108:111], v[142:145]
	v_mfma_f32_16x16x32_bf16 v[138:141], v[174:177], v[84:87], v[138:141]
	ds_read_b64_tr_b16 v[162:163], v206 offset:16384
	ds_read_b64_tr_b16 v[164:165], v206 offset:20480
	ds_read_b64_tr_b16 v[166:167], v207 offset:16384
	ds_read_b64_tr_b16 v[168:169], v207 offset:20480
	ds_read_b64_tr_b16 v[170:171], v208 offset:16384
	ds_read_b64_tr_b16 v[172:173], v208 offset:20480
	s_nop 7
	v_max3_f32 v233, v114, v115, v116
	v_max_f32_e32 v233, v233, v117
	v_max3_f32 v234, v118, v119, v120
	v_max_f32_e32 v234, v234, v121
	v_max3_f32 v233, v233, v122, v123
	v_max3_f32 v233, v233, v124, v125
	v_max3_f32 v234, v234, v126, v127
	v_max3_f32 v234, v234, v128, v129
	v_max3_f32 v233, v233, v130, v131
	v_max3_f32 v233, v233, v132, v133
	v_max3_f32 v234, v234, v134, v135
	v_max3_f32 v234, v234, v136, v137
	v_max3_f32 v233, v233, v138, v139
	v_max3_f32 v233, v233, v140, v141
	v_max3_f32 v234, v234, v142, v143
	v_max3_f32 v234, v234, v144, v145
	v_max_f32_e32 v235, v233, v234
	v_cmp_ge_f32_e32 vcc, s38, v235
	s_cmp_eq_u64 vcc, exec
	s_cbranch_scc0 .Lat_rare_1
; __device__ __forceinline__ void finishSM(f32x16& p0, f32x16& p1, float alpha, float& l_reg, bf16x8& pa0, bf16x8& pa1, bf16x8& pa2, bf16x8& pa3) {
; #pragma unroll
;   for (int r = 0; r < 16; ++r) p1[r] = __builtin_amdgcn_exp2f(p1[r]);
;   float ps = 0;
; #pragma unroll
;   for (int r = 0; r < 16; ++r) ps += p0[r];
; #pragma unroll
;   for (int r = 0; r < 16; ++r) ps += p1[r];
;   { auto rr = __builtin_amdgcn_permlane32_swap(__float_as_uint(ps), __float_as_uint(ps), false, false);
;     ps = __uint_as_float(rr[0]) + __uint_as_float(rr[1]); }
;   l_reg = l_reg * alpha + ps;
;     ...
;   PK4(p0, 0, pa0); PK4(p0, 8, pa1); PK4(p1, 0, pa2); PK4(p1, 8, pa3);
;     ...
; }
; __device__ __forceinline__ void qkt(f32x16& p0, f32x16& p1, const char* Ks, const bf16x8* qr, const char* qL, int r32, int hi, float negm) {
; #pragma unroll
;   for (int r = 0; r < 16; ++r) { p0[r] = negm; p1[r] = negm; }
; #pragma unroll
;   for (int d0 = 0; d0 < 12; ++d0) { int cb = (d0 * 16 + hi * 8) * 2;
;     bf16x8 b0 = *reinterpret_cast<const bf16x8*>(Ks + KSWZ(r32, cb));
;     bf16x8 b1 = *reinterpret_cast<const bf16x8*>(Ks + KSWZ(32 + r32, cb));
;     const bf16x8 q = d0 < 8 ? qr[d0 < 8 ? d0 : 0] : *reinterpret_cast<const bf16x8*>(qL + (d0 - 8) * 1024);
;     p0 = __builtin_amdgcn_mfma_f32_32x32x16_bf16(b0, q, p0, 0, 0, 0);
;     p1 = __builtin_amdgcn_mfma_f32_32x32x16_bf16(b1, q, p1, 0, 0, 0); }
; }
; __device__ __forceinline__ int v_st(int k, int c) { const int kk = (k & ~0xC) | ((k & 4) << 1) | ((k & 8) >> 1); return ((kk >> 3) * 4 + (c >> 5)) * 512 + ((kk & 7) * 32 + (c & 31)) * 2; }
; __device__ __forceinline__ int v_rd_base(int lane) { return ((lane & 3) << 3) | (((lane >> 2) & 3) << 6) | (((lane >> 4) & 1) << 5) | (((lane >> 5) & 1) << 8); }
; template <int OFF> __device__ __forceinline__ s16x4 tr_read(int vb) {
;   s16x4 r; asm volatile("ds_read_b64_tr_b16 %0, %1 offset:%2" : "=&v"(r) : "v"(vb), "i"(OFF) : "memory"); return r;
; }
; template <int D0> __device__ __forceinline__ void pv_one(f32x16& od, int vb, bf16x8 pa0, bf16x8 pa1, bf16x8 pa2, bf16x8 pa3) {
;   const s16x4 l0 = tr_read<v_rd_off(D0, 0, 0)>(vb), h0 = tr_read<v_rd_off(D0, 0, 1)>(vb), l1 = tr_read<v_rd_off(D0, 1, 0)>(vb), h1 = tr_read<v_rd_off(D0, 1, 1)>(vb);
;   const s16x4 l2 = tr_read<v_rd_off(D0, 2, 0)>(vb), h2 = tr_read<v_rd_off(D0, 2, 1)>(vb), l3 = tr_read<v_rd_off(D0, 3, 0)>(vb), h3 = tr_read<v_rd_off(D0, 3, 1)>(vb);
.Lat_cont_1:
	v_exp_f32_e32 v114, v114
	v_exp_f32_e32 v115, v115
	v_exp_f32_e32 v116, v116
	v_exp_f32_e32 v117, v117
	v_add_f32_e32 v222, v222, v114
	v_add_f32_e32 v222, v222, v115
	v_add_f32_e32 v222, v222, v116
	v_add_f32_e32 v222, v222, v117
	v_exp_f32_e32 v122, v122
	v_exp_f32_e32 v123, v123
	v_exp_f32_e32 v124, v124
	v_exp_f32_e32 v125, v125
	v_add_f32_e32 v222, v222, v122
	v_add_f32_e32 v222, v222, v123
	v_add_f32_e32 v222, v222, v124
	v_add_f32_e32 v222, v222, v125
	v_cvt_pk_bf16_f32 v146, v114, v115
	v_cvt_pk_bf16_f32 v147, v116, v117
	v_cvt_pk_bf16_f32 v148, v122, v123
	v_cvt_pk_bf16_f32 v149, v124, v125
	v_exp_f32_e32 v118, v118
	v_exp_f32_e32 v119, v119
	v_exp_f32_e32 v120, v120
	v_exp_f32_e32 v121, v121
	v_add_f32_e32 v223, v223, v118
	v_add_f32_e32 v223, v223, v119
	v_add_f32_e32 v223, v223, v120
	v_add_f32_e32 v223, v223, v121
	v_exp_f32_e32 v126, v126
	v_exp_f32_e32 v127, v127
	v_exp_f32_e32 v128, v128
	v_exp_f32_e32 v129, v129
	v_add_f32_e32 v223, v223, v126
	v_add_f32_e32 v223, v223, v127
	v_add_f32_e32 v223, v223, v128
	v_add_f32_e32 v223, v223, v129
	v_cvt_pk_bf16_f32 v154, v118, v119
	v_cvt_pk_bf16_f32 v155, v120, v121
	v_cvt_pk_bf16_f32 v156, v126, v127
	v_cvt_pk_bf16_f32 v157, v128, v129
	s_nop 1
	s_waitcnt lgkmcnt(4)
	v_mfma_f32_16x16x32_bf16 v[0:3], v[146:149], v[162:165], v[0:3]
	v_mfma_f32_16x16x32_bf16 v[32:35], v[154:157], v[162:165], v[32:35]
	ds_read_b64_tr_b16 v[174:175], v209 offset:16384
	ds_read_b64_tr_b16 v[176:177], v209 offset:20480
	v_exp_f32_e32 v130, v130
	v_exp_f32_e32 v131, v131
	v_exp_f32_e32 v132, v132
	v_exp_f32_e32 v133, v133
	v_add_f32_e32 v222, v222, v130
	s_waitcnt lgkmcnt(4)
	v_mfma_f32_16x16x32_bf16 v[36:39], v[154:157], v[166:169], v[36:39]
	v_mfma_f32_16x16x32_bf16 v[4:7], v[146:149], v[166:169], v[4:7]
	ds_read_b64_tr_b16 v[162:163], v210 offset:16384
	ds_read_b64_tr_b16 v[164:165], v210 offset:20480
	v_add_f32_e32 v222, v222, v131
	v_add_f32_e32 v222, v222, v132
	v_add_f32_e32 v222, v222, v133
	v_exp_f32_e32 v138, v138
	v_exp_f32_e32 v139, v139
	s_waitcnt lgkmcnt(4)
	v_mfma_f32_16x16x32_bf16 v[8:11], v[146:149], v[170:173], v[8:11]
	v_mfma_f32_16x16x32_bf16 v[40:43], v[154:157], v[170:173], v[40:43]
	ds_read_b64_tr_b16 v[166:167], v211 offset:16384
	ds_read_b64_tr_b16 v[168:169], v211 offset:20480
	v_exp_f32_e32 v140, v140
	v_exp_f32_e32 v141, v141
	v_add_f32_e32 v222, v222, v138
	v_add_f32_e32 v222, v222, v139
	v_add_f32_e32 v222, v222, v140
	s_waitcnt lgkmcnt(4)
	v_mfma_f32_16x16x32_bf16 v[44:47], v[154:157], v[174:177], v[44:47]
	v_mfma_f32_16x16x32_bf16 v[12:15], v[146:149], v[174:177], v[12:15]
	ds_read_b64_tr_b16 v[170:171], v212 offset:16384
	ds_read_b64_tr_b16 v[172:173], v212 offset:20480
	v_add_f32_e32 v222, v222, v141
	v_cvt_pk_bf16_f32 v150, v130, v131
	v_cvt_pk_bf16_f32 v151, v132, v133
	v_cvt_pk_bf16_f32 v152, v138, v139
	v_cvt_pk_bf16_f32 v153, v140, v141
	s_waitcnt lgkmcnt(4)
	v_mfma_f32_16x16x32_bf16 v[16:19], v[146:149], v[162:165], v[16:19]
	v_mfma_f32_16x16x32_bf16 v[48:51], v[154:157], v[162:165], v[48:51]
	ds_read_b64_tr_b16 v[174:175], v213 offset:16384
	ds_read_b64_tr_b16 v[176:177], v213 offset:20480
	v_exp_f32_e32 v134, v134
	v_exp_f32_e32 v135, v135
	v_exp_f32_e32 v136, v136
	v_exp_f32_e32 v137, v137
	v_add_f32_e32 v223, v223, v134
	s_waitcnt lgkmcnt(4)
	v_mfma_f32_16x16x32_bf16 v[52:55], v[154:157], v[166:169], v[52:55]
	v_mfma_f32_16x16x32_bf16 v[20:23], v[146:149], v[166:169], v[20:23]
	ds_read_b64_tr_b16 v[162:163], v206 offset:24576
	ds_read_b64_tr_b16 v[164:165], v206 offset:28672
	v_add_f32_e32 v223, v223, v135
	v_add_f32_e32 v223, v223, v136
	v_add_f32_e32 v223, v223, v137
	v_exp_f32_e32 v142, v142
	v_exp_f32_e32 v143, v143
	s_waitcnt lgkmcnt(4)
	v_mfma_f32_16x16x32_bf16 v[24:27], v[146:149], v[170:173], v[24:27]
	v_mfma_f32_16x16x32_bf16 v[56:59], v[154:157], v[170:173], v[56:59]
	ds_read_b64_tr_b16 v[166:167], v207 offset:24576
	ds_read_b64_tr_b16 v[168:169], v207 offset:28672
	v_exp_f32_e32 v144, v144
	v_exp_f32_e32 v145, v145
	v_add_f32_e32 v223, v223, v142
	v_add_f32_e32 v223, v223, v143
	v_add_f32_e32 v223, v223, v144
	s_waitcnt lgkmcnt(4)
	v_mfma_f32_16x16x32_bf16 v[60:63], v[154:157], v[174:177], v[60:63]
	v_mfma_f32_16x16x32_bf16 v[28:31], v[146:149], v[174:177], v[28:31]
	ds_read_b64_tr_b16 v[170:171], v208 offset:24576
	ds_read_b64_tr_b16 v[172:173], v208 offset:28672
	v_add_f32_e32 v223, v223, v145
	v_cvt_pk_bf16_f32 v158, v134, v135
	v_cvt_pk_bf16_f32 v159, v136, v137
	v_cvt_pk_bf16_f32 v160, v142, v143
	v_cvt_pk_bf16_f32 v161, v144, v145
	s_waitcnt lgkmcnt(4)
	s_nop 1
	v_mfma_f32_16x16x32_bf16 v[0:3], v[150:153], v[162:165], v[0:3]
	v_mfma_f32_16x16x32_bf16 v[32:35], v[158:161], v[162:165], v[32:35]
	ds_read_b64_tr_b16 v[174:175], v209 offset:24576
	ds_read_b64_tr_b16 v[176:177], v209 offset:28672
	s_waitcnt lgkmcnt(4)
	v_mfma_f32_16x16x32_bf16 v[36:39], v[158:161], v[166:169], v[36:39]
	v_mfma_f32_16x16x32_bf16 v[4:7], v[150:153], v[166:169], v[4:7]
	ds_read_b64_tr_b16 v[162:163], v210 offset:24576
	ds_read_b64_tr_b16 v[164:165], v210 offset:28672
	s_waitcnt lgkmcnt(4)
	v_mfma_f32_16x16x32_bf16 v[8:11], v[150:153], v[170:173], v[8:11]
	v_mfma_f32_16x16x32_bf16 v[40:43], v[158:161], v[170:173], v[40:43]
	ds_read_b64_tr_b16 v[166:167], v211 offset:24576
	ds_read_b64_tr_b16 v[168:169], v211 offset:28672
	s_waitcnt lgkmcnt(4)
	v_mfma_f32_16x16x32_bf16 v[44:47], v[158:161], v[174:177], v[44:47]
	v_mfma_f32_16x16x32_bf16 v[12:15], v[150:153], v[174:177], v[12:15]
	ds_read_b64_tr_b16 v[170:171], v212 offset:24576
	ds_read_b64_tr_b16 v[172:173], v212 offset:28672
	s_waitcnt lgkmcnt(4)
; #define SBAR() __builtin_amdgcn_sched_barrier(0)
; #define SLOAD(i, k0) do { sr_[i].vs0 = *(const bf16x8*)(&Vh[(long)((k0) + sr) * 128 + sc]); sr_[i].vs1 = *(const bf16x8*)(&Vh[(long)((k0) + 32 + sr) * 128 + sc]); \
;     sr_[i].ks0 = *(const bf16x8*)(&Kn[(long)((k0) + sr) * 128 + sc]); sr_[i].ks1 = *(const bf16x8*)(&Kn[(long)((k0) + 32 + sr) * 128 + sc]); \
;     sr_[i].ks2 = *(const bf16x8*)(&Kr[(long)((k0) + rr) * 64 + rc]); } while (0)
; #define SWRITE(b, i) do { *(bf16x8*)(V_lds + (b) * SHM_V + vst0) = sr_[i].vs0; *(bf16x8*)(V_lds + (b) * SHM_V + vst1) = sr_[i].vs1; \
;     *(bf16x8*)(K_lds + (b) * SHM_K + kst0) = sr_[i].ks0; *(bf16x8*)(K_lds + (b) * SHM_K + kst1) = sr_[i].ks1; *(bf16x8*)(K_lds + (b) * SHM_K + kst2) = sr_[i].ks2; } while (0)
; #define SWAIT() do { if constexpr (SDEPTH == 2) asm volatile("s_waitcnt vmcnt(5)" ::: "memory"); else asm volatile("s_waitcnt vmcnt(0)" ::: "memory"); } while (0)
; __device__ __forceinline__ void qkt(f32x16& p0, f32x16& p1, const char* Ks, const bf16x8* qr, const char* qL, int r32, int hi, float negm) {
; #pragma unroll
;   for (int r = 0; r < 16; ++r) { p0[r] = negm; p1[r] = negm; }
; #pragma unroll
;   for (int d0 = 0; d0 < 12; ++d0) { int cb = (d0 * 16 + hi * 8) * 2;
;     bf16x8 b0 = *reinterpret_cast<const bf16x8*>(Ks + KSWZ(r32, cb));
;     bf16x8 b1 = *reinterpret_cast<const bf16x8*>(Ks + KSWZ(32 + r32, cb));
;     const bf16x8 q = d0 < 8 ? qr[d0 < 8 ? d0 : 0] : *reinterpret_cast<const bf16x8*>(qL + (d0 - 8) * 1024);
;     p0 = __builtin_amdgcn_mfma_f32_32x32x16_bf16(b0, q, p0, 0, 0, 0);
;     p1 = __builtin_amdgcn_mfma_f32_32x32x16_bf16(b1, q, p1, 0, 0, 0); }
; }
; __device__ __forceinline__ void attn_unit(const bf16_t* __restrict__ Qb, const bf16_t* __restrict__ Kn, const bf16_t* __restrict__ Kr, const bf16_t* __restrict__ Vh,
;                                           bf16_t* __restrict__ Ob, char* lds) {
;     ...
;     SLOAD(SO, (j + SDEPTH) * KVBLK); SBAR();
;     pv_d0(o, vb0, pa0, pa1, pa2, pa3); partialSM<false>(pB0, pB1, m_reg, alB);
;     __syncthreads(); SWAIT(); SWRITE(0, SE);
;     RESC(alB); __syncthreads();
;     SBAR(); qkt(pA0, pA1, K_lds, qr, qL, r32, hi, -m_reg);
	v_mfma_f32_16x16x32_bf16 v[16:19], v[150:153], v[162:165], v[16:19]
	v_mfma_f32_16x16x32_bf16 v[48:51], v[158:161], v[162:165], v[48:51]
	ds_read_b64_tr_b16 v[174:175], v213 offset:24576
	ds_read_b64_tr_b16 v[176:177], v213 offset:28672
	s_waitcnt lgkmcnt(4)
	v_mfma_f32_16x16x32_bf16 v[52:55], v[158:161], v[166:169], v[52:55]
	v_mfma_f32_16x16x32_bf16 v[20:23], v[150:153], v[166:169], v[20:23]
	s_waitcnt vmcnt(0)
	ds_write_b128 v214, v[178:181] offset:32768
	ds_write_b128 v215, v[182:185] offset:32768
	ds_write_b128 v216, v[196:199] offset:32768
	ds_write_b128 v217, v[186:189] offset:0
	ds_write_b128 v217, v[190:193] offset:8192
	global_load_dwordx4 v[178:181], v218, s[22:23]
	global_load_dwordx4 v[182:185], v218, s[24:25]
	global_load_dwordx4 v[196:199], v218, s[34:35]
	global_load_dwordx4 v[186:189], v218, s[26:27]
	global_load_dwordx4 v[190:193], v218, s[30:31]
	s_add_u32 s22, s22, 16384
	s_addc_u32 s23, s23, 0
	s_add_u32 s24, s24, 16384
	s_addc_u32 s25, s25, 0
	s_add_u32 s26, s26, 16384
	s_addc_u32 s27, s27, 0
	s_add_u32 s30, s30, 16384
	s_addc_u32 s31, s31, 0
	s_add_u32 s34, s34, 8192
	s_addc_u32 s35, s35, 0
	s_waitcnt lgkmcnt(7)
	v_mfma_f32_16x16x32_bf16 v[24:27], v[150:153], v[170:173], v[24:27]
	v_mfma_f32_16x16x32_bf16 v[56:59], v[158:161], v[170:173], v[56:59]
	s_waitcnt lgkmcnt(5)
	v_mfma_f32_16x16x32_bf16 v[60:63], v[158:161], v[174:177], v[60:63]
	v_mfma_f32_16x16x32_bf16 v[28:31], v[150:153], v[174:177], v[28:31]
	s_waitcnt lgkmcnt(0)
	s_barrier
	ds_read_b128 v[162:165], v202 offset:32768
	ds_read_b128 v[166:169], v202 offset:38912
	ds_read_b128 v[170:173], v202 offset:45056
	s_waitcnt lgkmcnt(2)
	v_mfma_f32_16x16x32_bf16 v[114:117], v[162:165], v[64:67], v[224:227]
	v_mfma_f32_16x16x32_bf16 v[118:121], v[162:165], v[88:91], v[228:231]
	ds_read_b128 v[174:177], v202 offset:51200
	s_waitcnt lgkmcnt(2)
	v_mfma_f32_16x16x32_bf16 v[126:129], v[166:169], v[88:91], v[228:231]
	v_mfma_f32_16x16x32_bf16 v[122:125], v[166:169], v[64:67], v[224:227]
	ds_read_b128 v[162:165], v203 offset:32768
	s_waitcnt lgkmcnt(2)
	v_mfma_f32_16x16x32_bf16 v[130:133], v[170:173], v[64:67], v[224:227]
	v_mfma_f32_16x16x32_bf16 v[134:137], v[170:173], v[88:91], v[228:231]
	ds_read_b128 v[166:169], v203 offset:38912
	s_waitcnt lgkmcnt(2)
	v_mfma_f32_16x16x32_bf16 v[142:145], v[174:177], v[88:91], v[228:231]
	v_mfma_f32_16x16x32_bf16 v[138:141], v[174:177], v[64:67], v[224:227]
	ds_read_b128 v[170:173], v203 offset:45056
	s_waitcnt lgkmcnt(2)
	v_mfma_f32_16x16x32_bf16 v[114:117], v[162:165], v[68:71], v[114:117]
	v_mfma_f32_16x16x32_bf16 v[118:121], v[162:165], v[92:95], v[118:121]
	ds_read_b128 v[174:177], v203 offset:51200
	s_waitcnt lgkmcnt(2)
	v_mfma_f32_16x16x32_bf16 v[126:129], v[166:169], v[92:95], v[126:129]
	v_mfma_f32_16x16x32_bf16 v[122:125], v[166:169], v[68:71], v[122:125]
	ds_read_b128 v[162:165], v202 offset:32896
	s_waitcnt lgkmcnt(2)
	v_mfma_f32_16x16x32_bf16 v[130:133], v[170:173], v[68:71], v[130:133]
	v_mfma_f32_16x16x32_bf16 v[134:137], v[170:173], v[92:95], v[134:137]
	ds_read_b128 v[166:169], v202 offset:39040
	s_waitcnt lgkmcnt(2)
	v_mfma_f32_16x16x32_bf16 v[142:145], v[174:177], v[92:95], v[142:145]
	v_mfma_f32_16x16x32_bf16 v[138:141], v[174:177], v[68:71], v[138:141]
	ds_read_b128 v[170:173], v202 offset:45184
	s_waitcnt lgkmcnt(2)
	v_mfma_f32_16x16x32_bf16 v[114:117], v[162:165], v[72:75], v[114:117]
	v_mfma_f32_16x16x32_bf16 v[118:121], v[162:165], v[96:99], v[118:121]
	ds_read_b128 v[174:177], v202 offset:51328
	s_waitcnt lgkmcnt(2)
	v_mfma_f32_16x16x32_bf16 v[126:129], v[166:169], v[96:99], v[126:129]
	v_mfma_f32_16x16x32_bf16 v[122:125], v[166:169], v[72:75], v[122:125]
	ds_read_b128 v[162:165], v203 offset:32896
	s_waitcnt lgkmcnt(2)
	v_mfma_f32_16x16x32_bf16 v[130:133], v[170:173], v[72:75], v[130:133]
	v_mfma_f32_16x16x32_bf16 v[134:137], v[170:173], v[96:99], v[134:137]
	ds_read_b128 v[166:169], v203 offset:39040
	s_waitcnt lgkmcnt(2)
	v_mfma_f32_16x16x32_bf16 v[142:145], v[174:177], v[96:99], v[142:145]
	v_mfma_f32_16x16x32_bf16 v[138:141], v[174:177], v[72:75], v[138:141]
	ds_read_b128 v[170:173], v203 offset:45184
	s_waitcnt lgkmcnt(2)
	v_mfma_f32_16x16x32_bf16 v[114:117], v[162:165], v[76:79], v[114:117]
	v_mfma_f32_16x16x32_bf16 v[118:121], v[162:165], v[100:103], v[118:121]
	ds_read_b128 v[174:177], v203 offset:51328
	s_waitcnt lgkmcnt(2)
	v_mfma_f32_16x16x32_bf16 v[126:129], v[166:169], v[100:103], v[126:129]
	v_mfma_f32_16x16x32_bf16 v[122:125], v[166:169], v[76:79], v[122:125]
	ds_read_b128 v[162:165], v202 offset:33024
	s_waitcnt lgkmcnt(2)
	v_mfma_f32_16x16x32_bf16 v[130:133], v[170:173], v[76:79], v[130:133]
	v_mfma_f32_16x16x32_bf16 v[134:137], v[170:173], v[100:103], v[134:137]
	ds_read_b128 v[166:169], v202 offset:39168
	s_waitcnt lgkmcnt(2)
	v_mfma_f32_16x16x32_bf16 v[142:145], v[174:177], v[100:103], v[142:145]
	v_mfma_f32_16x16x32_bf16 v[138:141], v[174:177], v[76:79], v[138:141]
	ds_read_b128 v[170:173], v202 offset:45312
	s_waitcnt lgkmcnt(2)
	v_mfma_f32_16x16x32_bf16 v[114:117], v[162:165], v[80:83], v[114:117]
	v_mfma_f32_16x16x32_bf16 v[118:121], v[162:165], v[104:107], v[118:121]
	ds_read_b128 v[174:177], v202 offset:51456
	s_waitcnt lgkmcnt(2)
	v_mfma_f32_16x16x32_bf16 v[126:129], v[166:169], v[104:107], v[126:129]
	v_mfma_f32_16x16x32_bf16 v[122:125], v[166:169], v[80:83], v[122:125]
	ds_read_b128 v[162:165], v203 offset:33024
	s_waitcnt lgkmcnt(2)
	v_mfma_f32_16x16x32_bf16 v[130:133], v[170:173], v[80:83], v[130:133]
	v_mfma_f32_16x16x32_bf16 v[134:137], v[170:173], v[104:107], v[134:137]
	ds_read_b128 v[166:169], v203 offset:39168
	s_waitcnt lgkmcnt(2)
; template <bool FIRST>
; __device__ __forceinline__ void partialSM(f32x16& p0, f32x16& p1, float& m_reg, float& alpha) {
;   constexpr float THR2 = THR * 1.4426950408889634f;
;   float pmax = p0[0];
; #pragma unroll
;   for (int r = 1; r < 16; ++r) pmax = fmaxf(pmax, p0[r]);
; #pragma unroll
;   for (int r = 0; r < 16; ++r) pmax = fmaxf(pmax, p1[r]);
;   { auto rr = __builtin_amdgcn_permlane32_swap(__float_as_uint(pmax), __float_as_uint(pmax), false, false);
;     pmax = fmaxf(__uint_as_float(rr[0]), __uint_as_float(rr[1])); }
;   if (!FIRST && __builtin_expect(__all(pmax <= THR2), 1)) { alpha = 1.f; }
;   else { const float d = FIRST ? pmax : fmaxf(pmax, 0.f); alpha = FIRST ? 1.f : __builtin_amdgcn_exp2f(-d); m_reg += d;
; #pragma unroll
;     for (int r = 0; r < 16; ++r) p0[r] -= d;
; #pragma unroll
;     for (int r = 0; r < 16; ++r) p1[r] -= d; }
; #pragma unroll
;   for (int r = 0; r < 16; ++r) p0[r] = __builtin_amdgcn_exp2f(p0[r]);
; }
; __device__ __forceinline__ void finishSM(f32x16& p0, f32x16& p1, float alpha, float& l_reg, bf16x8& pa0, bf16x8& pa1, bf16x8& pa2, bf16x8& pa3) {
; #pragma unroll
;   for (int r = 0; r < 16; ++r) p1[r] = __builtin_amdgcn_exp2f(p1[r]);
;   float ps = 0;
; #pragma unroll
;   for (int r = 0; r < 16; ++r) ps += p0[r];
; #pragma unroll
;   for (int r = 0; r < 16; ++r) ps += p1[r];
;   { auto rr = __builtin_amdgcn_permlane32_swap(__float_as_uint(ps), __float_as_uint(ps), false, false);
;     ps = __uint_as_float(rr[0]) + __uint_as_float(rr[1]); }
;   l_reg = l_reg * alpha + ps;
;     ...
;   PK4(p0, 0, pa0); PK4(p0, 8, pa1); PK4(p1, 0, pa2); PK4(p1, 8, pa3);
;     ...
; }
; __device__ __forceinline__ void qkt(f32x16& p0, f32x16& p1, const char* Ks, const bf16x8* qr, const char* qL, int r32, int hi, float negm) {
;     ...
;   for (int d0 = 0; d0 < 12; ++d0) { int cb = (d0 * 16 + hi * 8) * 2;
;     bf16x8 b0 = *reinterpret_cast<const bf16x8*>(Ks + KSWZ(r32, cb));
;     bf16x8 b1 = *reinterpret_cast<const bf16x8*>(Ks + KSWZ(32 + r32, cb));
;     const bf16x8 q = d0 < 8 ? qr[d0 < 8 ? d0 : 0] : *reinterpret_cast<const bf16x8*>(qL + (d0 - 8) * 1024);
;     p0 = __builtin_amdgcn_mfma_f32_32x32x16_bf16(b0, q, p0, 0, 0, 0);
;     p1 = __builtin_amdgcn_mfma_f32_32x32x16_bf16(b1, q, p1, 0, 0, 0); }
	v_mfma_f32_16x16x32_bf16 v[142:145], v[174:177], v[104:107], v[142:145]
	v_mfma_f32_16x16x32_bf16 v[138:141], v[174:177], v[80:83], v[138:141]
	ds_read_b128 v[170:173], v203 offset:45312
	s_waitcnt lgkmcnt(2)
	v_mfma_f32_16x16x32_bf16 v[114:117], v[162:165], v[84:87], v[114:117]
	v_mfma_f32_16x16x32_bf16 v[118:121], v[162:165], v[108:111], v[118:121]
	ds_read_b128 v[174:177], v203 offset:51456
	s_waitcnt lgkmcnt(2)
	v_mfma_f32_16x16x32_bf16 v[126:129], v[166:169], v[108:111], v[126:129]
	v_mfma_f32_16x16x32_bf16 v[122:125], v[166:169], v[84:87], v[122:125]
	s_waitcnt lgkmcnt(1)
	v_mfma_f32_16x16x32_bf16 v[130:133], v[170:173], v[84:87], v[130:133]
	v_mfma_f32_16x16x32_bf16 v[134:137], v[170:173], v[108:111], v[134:137]
	s_waitcnt lgkmcnt(0)
	v_mfma_f32_16x16x32_bf16 v[142:145], v[174:177], v[108:111], v[142:145]
	v_mfma_f32_16x16x32_bf16 v[138:141], v[174:177], v[84:87], v[138:141]
	ds_read_b64_tr_b16 v[162:163], v206 offset:0
	ds_read_b64_tr_b16 v[164:165], v206 offset:4096
	ds_read_b64_tr_b16 v[166:167], v207 offset:0
	ds_read_b64_tr_b16 v[168:169], v207 offset:4096
	ds_read_b64_tr_b16 v[170:171], v208 offset:0
	ds_read_b64_tr_b16 v[172:173], v208 offset:4096
	s_nop 7
	v_max3_f32 v233, v114, v115, v116
	v_max_f32_e32 v233, v233, v117
	v_max3_f32 v234, v118, v119, v120
	v_max_f32_e32 v234, v234, v121
	v_max3_f32 v233, v233, v122, v123
	v_max3_f32 v233, v233, v124, v125
	v_max3_f32 v234, v234, v126, v127
	v_max3_f32 v234, v234, v128, v129
	v_max3_f32 v233, v233, v130, v131
	v_max3_f32 v233, v233, v132, v133
	v_max3_f32 v234, v234, v134, v135
	v_max3_f32 v234, v234, v136, v137
	v_max3_f32 v233, v233, v138, v139
	v_max3_f32 v233, v233, v140, v141
	v_max3_f32 v234, v234, v142, v143
	v_max3_f32 v234, v234, v144, v145
	v_max_f32_e32 v235, v233, v234
	v_cmp_ge_f32_e32 vcc, s38, v235
	s_cmp_eq_u64 vcc, exec
	s_cbranch_scc0 .Lat_rare_2
.Lat_cont_2:
	v_exp_f32_e32 v114, v114
	v_exp_f32_e32 v115, v115
	v_exp_f32_e32 v116, v116
	v_exp_f32_e32 v117, v117
	v_add_f32_e32 v222, v222, v114
	v_add_f32_e32 v222, v222, v115
	v_add_f32_e32 v222, v222, v116
	v_add_f32_e32 v222, v222, v117
	v_exp_f32_e32 v122, v122
	v_exp_f32_e32 v123, v123
	v_exp_f32_e32 v124, v124
	v_exp_f32_e32 v125, v125
	v_add_f32_e32 v222, v222, v122
	v_add_f32_e32 v222, v222, v123
	v_add_f32_e32 v222, v222, v124
	v_add_f32_e32 v222, v222, v125
	v_cvt_pk_bf16_f32 v146, v114, v115
	v_cvt_pk_bf16_f32 v147, v116, v117
	v_cvt_pk_bf16_f32 v148, v122, v123
	v_cvt_pk_bf16_f32 v149, v124, v125
	v_exp_f32_e32 v118, v118
	v_exp_f32_e32 v119, v119
	v_exp_f32_e32 v120, v120
	v_exp_f32_e32 v121, v121
	v_add_f32_e32 v223, v223, v118
	v_add_f32_e32 v223, v223, v119
	v_add_f32_e32 v223, v223, v120
	v_add_f32_e32 v223, v223, v121
	v_exp_f32_e32 v126, v126
	v_exp_f32_e32 v127, v127
	v_exp_f32_e32 v128, v128
	v_exp_f32_e32 v129, v129
	v_add_f32_e32 v223, v223, v126
	v_add_f32_e32 v223, v223, v127
	v_add_f32_e32 v223, v223, v128
	v_add_f32_e32 v223, v223, v129
	v_cvt_pk_bf16_f32 v154, v118, v119
	v_cvt_pk_bf16_f32 v155, v120, v121
	v_cvt_pk_bf16_f32 v156, v126, v127
	v_cvt_pk_bf16_f32 v157, v128, v129
	s_nop 1
	s_waitcnt lgkmcnt(4)
	v_mfma_f32_16x16x32_bf16 v[0:3], v[146:149], v[162:165], v[0:3]
	v_mfma_f32_16x16x32_bf16 v[32:35], v[154:157], v[162:165], v[32:35]
	ds_read_b64_tr_b16 v[174:175], v209 offset:0
	ds_read_b64_tr_b16 v[176:177], v209 offset:4096
	v_exp_f32_e32 v130, v130
	v_exp_f32_e32 v131, v131
	v_exp_f32_e32 v132, v132
	v_exp_f32_e32 v133, v133
	v_add_f32_e32 v222, v222, v130
	s_waitcnt lgkmcnt(4)
	v_mfma_f32_16x16x32_bf16 v[36:39], v[154:157], v[166:169], v[36:39]
	v_mfma_f32_16x16x32_bf16 v[4:7], v[146:149], v[166:169], v[4:7]
	ds_read_b64_tr_b16 v[162:163], v210 offset:0
	ds_read_b64_tr_b16 v[164:165], v210 offset:4096
	v_add_f32_e32 v222, v222, v131
	v_add_f32_e32 v222, v222, v132
	v_add_f32_e32 v222, v222, v133
	v_exp_f32_e32 v138, v138
	v_exp_f32_e32 v139, v139
	s_waitcnt lgkmcnt(4)
	v_mfma_f32_16x16x32_bf16 v[8:11], v[146:149], v[170:173], v[8:11]
	v_mfma_f32_16x16x32_bf16 v[40:43], v[154:157], v[170:173], v[40:43]
	ds_read_b64_tr_b16 v[166:167], v211 offset:0
	ds_read_b64_tr_b16 v[168:169], v211 offset:4096
	v_exp_f32_e32 v140, v140
	v_exp_f32_e32 v141, v141
	v_add_f32_e32 v222, v222, v138
	v_add_f32_e32 v222, v222, v139
	v_add_f32_e32 v222, v222, v140
	s_waitcnt lgkmcnt(4)
	v_mfma_f32_16x16x32_bf16 v[44:47], v[154:157], v[174:177], v[44:47]
	v_mfma_f32_16x16x32_bf16 v[12:15], v[146:149], v[174:177], v[12:15]
	ds_read_b64_tr_b16 v[170:171], v212 offset:0
	ds_read_b64_tr_b16 v[172:173], v212 offset:4096
	v_add_f32_e32 v222, v222, v141
	v_cvt_pk_bf16_f32 v150, v130, v131
	v_cvt_pk_bf16_f32 v151, v132, v133
	v_cvt_pk_bf16_f32 v152, v138, v139
	v_cvt_pk_bf16_f32 v153, v140, v141
	s_waitcnt lgkmcnt(4)
	v_mfma_f32_16x16x32_bf16 v[16:19], v[146:149], v[162:165], v[16:19]
	v_mfma_f32_16x16x32_bf16 v[48:51], v[154:157], v[162:165], v[48:51]
	ds_read_b64_tr_b16 v[174:175], v213 offset:0
	ds_read_b64_tr_b16 v[176:177], v213 offset:4096
	v_exp_f32_e32 v134, v134
	v_exp_f32_e32 v135, v135
	v_exp_f32_e32 v136, v136
	v_exp_f32_e32 v137, v137
	v_add_f32_e32 v223, v223, v134
	s_waitcnt lgkmcnt(4)
	v_mfma_f32_16x16x32_bf16 v[52:55], v[154:157], v[166:169], v[52:55]
	v_mfma_f32_16x16x32_bf16 v[20:23], v[146:149], v[166:169], v[20:23]
	ds_read_b64_tr_b16 v[162:163], v206 offset:8192
	ds_read_b64_tr_b16 v[164:165], v206 offset:12288
	v_add_f32_e32 v223, v223, v135
	v_add_f32_e32 v223, v223, v136
	v_add_f32_e32 v223, v223, v137
	v_exp_f32_e32 v142, v142
	v_exp_f32_e32 v143, v143
	s_waitcnt lgkmcnt(4)
; #define SBAR() __builtin_amdgcn_sched_barrier(0)
; template <int D0> __device__ __forceinline__ void pv_one(f32x16& od, int vb, bf16x8 pa0, bf16x8 pa1, bf16x8 pa2, bf16x8 pa3) {
;   const s16x4 l0 = tr_read<v_rd_off(D0, 0, 0)>(vb), h0 = tr_read<v_rd_off(D0, 0, 1)>(vb), l1 = tr_read<v_rd_off(D0, 1, 0)>(vb), h1 = tr_read<v_rd_off(D0, 1, 1)>(vb);
;   const s16x4 l2 = tr_read<v_rd_off(D0, 2, 0)>(vb), h2 = tr_read<v_rd_off(D0, 2, 1)>(vb), l3 = tr_read<v_rd_off(D0, 3, 0)>(vb), h3 = tr_read<v_rd_off(D0, 3, 1)>(vb);
;   asm volatile("s_waitcnt lgkmcnt(0)" ::: "memory"); SBAR();
;     ...
;   od = __builtin_amdgcn_mfma_f32_32x32x16_bf16(pa0, PK(l0, h0), od, 0, 0, 0);
;   od = __builtin_amdgcn_mfma_f32_32x32x16_bf16(pa1, PK(l1, h1), od, 0, 0, 0);
;   od = __builtin_amdgcn_mfma_f32_32x32x16_bf16(pa2, PK(l2, h2), od, 0, 0, 0);
;   od = __builtin_amdgcn_mfma_f32_32x32x16_bf16(pa3, PK(l3, h3), od, 0, 0, 0);
;     ...
; }
; __device__ __forceinline__ void pv_d0(f32x16* o, int vb, bf16x8 pa0, bf16x8 pa1, bf16x8 pa2, bf16x8 pa3) {
;   pv_one<0>(o[0], vb, pa0, pa1, pa2, pa3); pv_one<1>(o[1], vb, pa0, pa1, pa2, pa3); pv_one<2>(o[2], vb, pa0, pa1, pa2, pa3); pv_one<3>(o[3], vb, pa0, pa1, pa2, pa3);
; }
; __device__ __forceinline__ void attn_unit(const bf16_t* __restrict__ Qb, const bf16_t* __restrict__ Kn, const bf16_t* __restrict__ Kr, const bf16_t* __restrict__ Vh,
;                                           bf16_t* __restrict__ Ob, char* lds) {
;     ...
;   for (int j = 1; j + 1 < NT; j += 2) {
;     SBAR(); qkt(pB0, pB1, K_lds + SHM_K, qr, qL, r32, hi, -m_reg);
;     finishSM(pA0, pA1, alA, l_reg, pa0, pa1, pa2, pa3); SBAR();
;     SLOAD(SO, (j + SDEPTH) * KVBLK); SBAR();
;     pv_d0(o, vb0, pa0, pa1, pa2, pa3); partialSM<false>(pB0, pB1, m_reg, alB);
;     __syncthreads(); SWAIT(); SWRITE(0, SE);
;     RESC(alB); __syncthreads();
;     SBAR(); qkt(pA0, pA1, K_lds, qr, qL, r32, hi, -m_reg);
;     finishSM(pB0, pB1, alB, l_reg, pa0, pa1, pa2, pa3); SBAR();
;     if (SDEPTH == 1 || j + 3 < NT) SLOAD(SE, (j + 1 + SDEPTH) * KVBLK); SBAR();
;     pv_d0(o, vb0 + (int)SHM_V, pa0, pa1, pa2, pa3); partialSM<false>(pA0, pA1, m_reg, alA);
;     __syncthreads(); SWAIT(); SWRITE(1, SO);
;     RESC(alA); __syncthreads();
;   }
;   SBAR(); qkt(pB0, pB1, K_lds + SHM_K, qr, qL, r32, hi, -m_reg);
	v_mfma_f32_16x16x32_bf16 v[24:27], v[146:149], v[170:173], v[24:27]
	v_mfma_f32_16x16x32_bf16 v[56:59], v[154:157], v[170:173], v[56:59]
	ds_read_b64_tr_b16 v[166:167], v207 offset:8192
	ds_read_b64_tr_b16 v[168:169], v207 offset:12288
	v_exp_f32_e32 v144, v144
	v_exp_f32_e32 v145, v145
	v_add_f32_e32 v223, v223, v142
	v_add_f32_e32 v223, v223, v143
	v_add_f32_e32 v223, v223, v144
	s_waitcnt lgkmcnt(4)
	v_mfma_f32_16x16x32_bf16 v[60:63], v[154:157], v[174:177], v[60:63]
	v_mfma_f32_16x16x32_bf16 v[28:31], v[146:149], v[174:177], v[28:31]
	ds_read_b64_tr_b16 v[170:171], v208 offset:8192
	ds_read_b64_tr_b16 v[172:173], v208 offset:12288
	v_add_f32_e32 v223, v223, v145
	v_cvt_pk_bf16_f32 v158, v134, v135
	v_cvt_pk_bf16_f32 v159, v136, v137
	v_cvt_pk_bf16_f32 v160, v142, v143
	v_cvt_pk_bf16_f32 v161, v144, v145
	s_waitcnt lgkmcnt(4)
	s_nop 1
	v_mfma_f32_16x16x32_bf16 v[0:3], v[150:153], v[162:165], v[0:3]
	v_mfma_f32_16x16x32_bf16 v[32:35], v[158:161], v[162:165], v[32:35]
	ds_read_b64_tr_b16 v[174:175], v209 offset:8192
	ds_read_b64_tr_b16 v[176:177], v209 offset:12288
	s_waitcnt lgkmcnt(4)
	v_mfma_f32_16x16x32_bf16 v[36:39], v[158:161], v[166:169], v[36:39]
	v_mfma_f32_16x16x32_bf16 v[4:7], v[150:153], v[166:169], v[4:7]
	ds_read_b64_tr_b16 v[162:163], v210 offset:8192
	ds_read_b64_tr_b16 v[164:165], v210 offset:12288
	s_waitcnt lgkmcnt(4)
	v_mfma_f32_16x16x32_bf16 v[8:11], v[150:153], v[170:173], v[8:11]
	v_mfma_f32_16x16x32_bf16 v[40:43], v[158:161], v[170:173], v[40:43]
	ds_read_b64_tr_b16 v[166:167], v211 offset:8192
	ds_read_b64_tr_b16 v[168:169], v211 offset:12288
	s_waitcnt lgkmcnt(4)
	v_mfma_f32_16x16x32_bf16 v[44:47], v[158:161], v[174:177], v[44:47]
	v_mfma_f32_16x16x32_bf16 v[12:15], v[150:153], v[174:177], v[12:15]
	ds_read_b64_tr_b16 v[170:171], v212 offset:8192
	ds_read_b64_tr_b16 v[172:173], v212 offset:12288
	s_waitcnt lgkmcnt(4)
	v_mfma_f32_16x16x32_bf16 v[16:19], v[150:153], v[162:165], v[16:19]
	v_mfma_f32_16x16x32_bf16 v[48:51], v[158:161], v[162:165], v[48:51]
	ds_read_b64_tr_b16 v[174:175], v213 offset:8192
	ds_read_b64_tr_b16 v[176:177], v213 offset:12288
	s_waitcnt lgkmcnt(4)
	v_mfma_f32_16x16x32_bf16 v[52:55], v[158:161], v[166:169], v[52:55]
	v_mfma_f32_16x16x32_bf16 v[20:23], v[150:153], v[166:169], v[20:23]
	s_waitcnt vmcnt(0)
	ds_write_b128 v214, v[178:181] offset:57344
	ds_write_b128 v215, v[182:185] offset:57344
	ds_write_b128 v216, v[196:199] offset:57344
	ds_write_b128 v217, v[186:189] offset:16384
	ds_write_b128 v217, v[190:193] offset:24576
	global_load_dwordx4 v[178:181], v218, s[22:23]
	global_load_dwordx4 v[182:185], v218, s[24:25]
	global_load_dwordx4 v[196:199], v218, s[34:35]
	global_load_dwordx4 v[186:189], v218, s[26:27]
	global_load_dwordx4 v[190:193], v218, s[30:31]
	s_add_u32 s22, s22, 16384
	s_addc_u32 s23, s23, 0
	s_add_u32 s24, s24, 16384
	s_addc_u32 s25, s25, 0
	s_add_u32 s26, s26, 16384
	s_addc_u32 s27, s27, 0
	s_add_u32 s30, s30, 16384
	s_addc_u32 s31, s31, 0
	s_add_u32 s34, s34, 8192
	s_addc_u32 s35, s35, 0
	s_waitcnt lgkmcnt(7)
	v_mfma_f32_16x16x32_bf16 v[24:27], v[150:153], v[170:173], v[24:27]
	v_mfma_f32_16x16x32_bf16 v[56:59], v[158:161], v[170:173], v[56:59]
	s_waitcnt lgkmcnt(5)
	v_mfma_f32_16x16x32_bf16 v[60:63], v[158:161], v[174:177], v[60:63]
	v_mfma_f32_16x16x32_bf16 v[28:31], v[150:153], v[174:177], v[28:31]
	s_waitcnt lgkmcnt(0)
	s_barrier
	s_sub_u32 s39, s39, 1
	s_cmp_lg_u32 s39, 0
	s_cbranch_scc1 .Lat_loop
	ds_read_b128 v[162:165], v204 offset:32768
	ds_read_b128 v[166:169], v204 offset:38912
	ds_read_b128 v[170:173], v204 offset:45056
	s_waitcnt lgkmcnt(2)
	v_mfma_f32_16x16x32_bf16 v[114:117], v[162:165], v[64:67], v[224:227]
	v_mfma_f32_16x16x32_bf16 v[118:121], v[162:165], v[88:91], v[228:231]
	ds_read_b128 v[174:177], v204 offset:51200
	s_waitcnt lgkmcnt(2)
	v_mfma_f32_16x16x32_bf16 v[126:129], v[166:169], v[88:91], v[228:231]
	v_mfma_f32_16x16x32_bf16 v[122:125], v[166:169], v[64:67], v[224:227]
	ds_read_b128 v[162:165], v205 offset:32768
	s_waitcnt lgkmcnt(2)
	v_mfma_f32_16x16x32_bf16 v[130:133], v[170:173], v[64:67], v[224:227]
	v_mfma_f32_16x16x32_bf16 v[134:137], v[170:173], v[88:91], v[228:231]
	ds_read_b128 v[166:169], v205 offset:38912
	s_waitcnt lgkmcnt(2)
	v_mfma_f32_16x16x32_bf16 v[142:145], v[174:177], v[88:91], v[228:231]
	v_mfma_f32_16x16x32_bf16 v[138:141], v[174:177], v[64:67], v[224:227]
	ds_read_b128 v[170:173], v205 offset:45056
	s_waitcnt lgkmcnt(2)
	v_mfma_f32_16x16x32_bf16 v[114:117], v[162:165], v[68:71], v[114:117]
	v_mfma_f32_16x16x32_bf16 v[118:121], v[162:165], v[92:95], v[118:121]
	ds_read_b128 v[174:177], v205 offset:51200
	s_waitcnt lgkmcnt(2)
	v_mfma_f32_16x16x32_bf16 v[126:129], v[166:169], v[92:95], v[126:129]
	v_mfma_f32_16x16x32_bf16 v[122:125], v[166:169], v[68:71], v[122:125]
	ds_read_b128 v[162:165], v204 offset:32896
	s_waitcnt lgkmcnt(2)
	v_mfma_f32_16x16x32_bf16 v[130:133], v[170:173], v[68:71], v[130:133]
	v_mfma_f32_16x16x32_bf16 v[134:137], v[170:173], v[92:95], v[134:137]
	ds_read_b128 v[166:169], v204 offset:39040
	s_waitcnt lgkmcnt(2)
	v_mfma_f32_16x16x32_bf16 v[142:145], v[174:177], v[92:95], v[142:145]
	v_mfma_f32_16x16x32_bf16 v[138:141], v[174:177], v[68:71], v[138:141]
	ds_read_b128 v[170:173], v204 offset:45184
	s_waitcnt lgkmcnt(2)
	v_mfma_f32_16x16x32_bf16 v[114:117], v[162:165], v[72:75], v[114:117]
	v_mfma_f32_16x16x32_bf16 v[118:121], v[162:165], v[96:99], v[118:121]
	ds_read_b128 v[174:177], v204 offset:51328
	s_waitcnt lgkmcnt(2)
	v_mfma_f32_16x16x32_bf16 v[126:129], v[166:169], v[96:99], v[126:129]
	v_mfma_f32_16x16x32_bf16 v[122:125], v[166:169], v[72:75], v[122:125]
	ds_read_b128 v[162:165], v205 offset:32896
	s_waitcnt lgkmcnt(2)
; __device__ __forceinline__ void finishSM(f32x16& p0, f32x16& p1, float alpha, float& l_reg, bf16x8& pa0, bf16x8& pa1, bf16x8& pa2, bf16x8& pa3) {
; #pragma unroll
;   for (int r = 0; r < 16; ++r) p1[r] = __builtin_amdgcn_exp2f(p1[r]);
;   float ps = 0;
; #pragma unroll
;   for (int r = 0; r < 16; ++r) ps += p0[r];
; #pragma unroll
;   for (int r = 0; r < 16; ++r) ps += p1[r];
;   { auto rr = __builtin_amdgcn_permlane32_swap(__float_as_uint(ps), __float_as_uint(ps), false, false);
;     ps = __uint_as_float(rr[0]) + __uint_as_float(rr[1]); }
;   l_reg = l_reg * alpha + ps;
;     ...
;   PK4(p0, 0, pa0); PK4(p0, 8, pa1); PK4(p1, 0, pa2); PK4(p1, 8, pa3);
;     ...
; }
; __device__ __forceinline__ void qkt(f32x16& p0, f32x16& p1, const char* Ks, const bf16x8* qr, const char* qL, int r32, int hi, float negm) {
; #pragma unroll
;   for (int r = 0; r < 16; ++r) { p0[r] = negm; p1[r] = negm; }
; #pragma unroll
;   for (int d0 = 0; d0 < 12; ++d0) { int cb = (d0 * 16 + hi * 8) * 2;
;     bf16x8 b0 = *reinterpret_cast<const bf16x8*>(Ks + KSWZ(r32, cb));
;     bf16x8 b1 = *reinterpret_cast<const bf16x8*>(Ks + KSWZ(32 + r32, cb));
;     const bf16x8 q = d0 < 8 ? qr[d0 < 8 ? d0 : 0] : *reinterpret_cast<const bf16x8*>(qL + (d0 - 8) * 1024);
;     p0 = __builtin_amdgcn_mfma_f32_32x32x16_bf16(b0, q, p0, 0, 0, 0);
;     p1 = __builtin_amdgcn_mfma_f32_32x32x16_bf16(b1, q, p1, 0, 0, 0); }
	v_mfma_f32_16x16x32_bf16 v[130:133], v[170:173], v[72:75], v[130:133]
	v_mfma_f32_16x16x32_bf16 v[134:137], v[170:173], v[96:99], v[134:137]
	ds_read_b128 v[166:169], v205 offset:39040
	s_waitcnt lgkmcnt(2)
	v_mfma_f32_16x16x32_bf16 v[142:145], v[174:177], v[96:99], v[142:145]
	v_mfma_f32_16x16x32_bf16 v[138:141], v[174:177], v[72:75], v[138:141]
	ds_read_b128 v[170:173], v205 offset:45184
	s_waitcnt lgkmcnt(2)
	v_mfma_f32_16x16x32_bf16 v[114:117], v[162:165], v[76:79], v[114:117]
	v_mfma_f32_16x16x32_bf16 v[118:121], v[162:165], v[100:103], v[118:121]
	ds_read_b128 v[174:177], v205 offset:51328
	s_waitcnt lgkmcnt(2)
	v_mfma_f32_16x16x32_bf16 v[126:129], v[166:169], v[100:103], v[126:129]
	v_mfma_f32_16x16x32_bf16 v[122:125], v[166:169], v[76:79], v[122:125]
	ds_read_b128 v[162:165], v204 offset:33024
	s_waitcnt lgkmcnt(2)
	v_mfma_f32_16x16x32_bf16 v[130:133], v[170:173], v[76:79], v[130:133]
	v_mfma_f32_16x16x32_bf16 v[134:137], v[170:173], v[100:103], v[134:137]
	ds_read_b128 v[166:169], v204 offset:39168
	s_waitcnt lgkmcnt(2)
	v_mfma_f32_16x16x32_bf16 v[142:145], v[174:177], v[100:103], v[142:145]
	v_mfma_f32_16x16x32_bf16 v[138:141], v[174:177], v[76:79], v[138:141]
	ds_read_b128 v[170:173], v204 offset:45312
	s_waitcnt lgkmcnt(2)
	v_mfma_f32_16x16x32_bf16 v[114:117], v[162:165], v[80:83], v[114:117]
	v_mfma_f32_16x16x32_bf16 v[118:121], v[162:165], v[104:107], v[118:121]
	ds_read_b128 v[174:177], v204 offset:51456
	s_waitcnt lgkmcnt(2)
	v_mfma_f32_16x16x32_bf16 v[126:129], v[166:169], v[104:107], v[126:129]
	v_mfma_f32_16x16x32_bf16 v[122:125], v[166:169], v[80:83], v[122:125]
	ds_read_b128 v[162:165], v205 offset:33024
	s_waitcnt lgkmcnt(2)
	v_mfma_f32_16x16x32_bf16 v[130:133], v[170:173], v[80:83], v[130:133]
	v_mfma_f32_16x16x32_bf16 v[134:137], v[170:173], v[104:107], v[134:137]
	ds_read_b128 v[166:169], v205 offset:39168
	s_waitcnt lgkmcnt(2)
	v_mfma_f32_16x16x32_bf16 v[142:145], v[174:177], v[104:107], v[142:145]
	v_mfma_f32_16x16x32_bf16 v[138:141], v[174:177], v[80:83], v[138:141]
	ds_read_b128 v[170:173], v205 offset:45312
	s_waitcnt lgkmcnt(2)
	v_mfma_f32_16x16x32_bf16 v[114:117], v[162:165], v[84:87], v[114:117]
	v_mfma_f32_16x16x32_bf16 v[118:121], v[162:165], v[108:111], v[118:121]
	ds_read_b128 v[174:177], v205 offset:51456
	s_waitcnt lgkmcnt(2)
	v_mfma_f32_16x16x32_bf16 v[126:129], v[166:169], v[108:111], v[126:129]
	v_mfma_f32_16x16x32_bf16 v[122:125], v[166:169], v[84:87], v[122:125]
	s_waitcnt lgkmcnt(1)
	v_mfma_f32_16x16x32_bf16 v[130:133], v[170:173], v[84:87], v[130:133]
	v_mfma_f32_16x16x32_bf16 v[134:137], v[170:173], v[108:111], v[134:137]
	s_waitcnt lgkmcnt(0)
	v_mfma_f32_16x16x32_bf16 v[142:145], v[174:177], v[108:111], v[142:145]
	v_mfma_f32_16x16x32_bf16 v[138:141], v[174:177], v[84:87], v[138:141]
	ds_read_b64_tr_b16 v[162:163], v206 offset:16384
	ds_read_b64_tr_b16 v[164:165], v206 offset:20480
	ds_read_b64_tr_b16 v[166:167], v207 offset:16384
	ds_read_b64_tr_b16 v[168:169], v207 offset:20480
	ds_read_b64_tr_b16 v[170:171], v208 offset:16384
	ds_read_b64_tr_b16 v[172:173], v208 offset:20480
	s_nop 7
	v_max3_f32 v233, v114, v115, v116
	v_max_f32_e32 v233, v233, v117
	v_max3_f32 v234, v118, v119, v120
	v_max_f32_e32 v234, v234, v121
	v_max3_f32 v233, v233, v122, v123
	v_max3_f32 v233, v233, v124, v125
	v_max3_f32 v234, v234, v126, v127
	v_max3_f32 v234, v234, v128, v129
	v_max3_f32 v233, v233, v130, v131
	v_max3_f32 v233, v233, v132, v133
	v_max3_f32 v234, v234, v134, v135
	v_max3_f32 v234, v234, v136, v137
	v_max3_f32 v233, v233, v138, v139
	v_max3_f32 v233, v233, v140, v141
	v_max3_f32 v234, v234, v142, v143
	v_max3_f32 v234, v234, v144, v145
	v_max_f32_e32 v235, v233, v234
	v_cmp_ge_f32_e32 vcc, s38, v235
	s_cmp_eq_u64 vcc, exec
	s_cbranch_scc0 .Lat_rare_3
.Lat_cont_3:
	v_exp_f32_e32 v114, v114
	v_exp_f32_e32 v115, v115
	v_exp_f32_e32 v116, v116
	v_exp_f32_e32 v117, v117
	v_add_f32_e32 v222, v222, v114
	v_add_f32_e32 v222, v222, v115
	v_add_f32_e32 v222, v222, v116
	v_add_f32_e32 v222, v222, v117
	v_exp_f32_e32 v122, v122
	v_exp_f32_e32 v123, v123
	v_exp_f32_e32 v124, v124
	v_exp_f32_e32 v125, v125
	v_add_f32_e32 v222, v222, v122
	v_add_f32_e32 v222, v222, v123
	v_add_f32_e32 v222, v222, v124
	v_add_f32_e32 v222, v222, v125
	v_cvt_pk_bf16_f32 v146, v114, v115
	v_cvt_pk_bf16_f32 v147, v116, v117
	v_cvt_pk_bf16_f32 v148, v122, v123
	v_cvt_pk_bf16_f32 v149, v124, v125
	v_exp_f32_e32 v118, v118
	v_exp_f32_e32 v119, v119
	v_exp_f32_e32 v120, v120
	v_exp_f32_e32 v121, v121
	v_add_f32_e32 v223, v223, v118
	v_add_f32_e32 v223, v223, v119
	v_add_f32_e32 v223, v223, v120
	v_add_f32_e32 v223, v223, v121
	v_exp_f32_e32 v126, v126
	v_exp_f32_e32 v127, v127
	v_exp_f32_e32 v128, v128
	v_exp_f32_e32 v129, v129
	v_add_f32_e32 v223, v223, v126
	v_add_f32_e32 v223, v223, v127
	v_add_f32_e32 v223, v223, v128
	v_add_f32_e32 v223, v223, v129
	v_cvt_pk_bf16_f32 v154, v118, v119
	v_cvt_pk_bf16_f32 v155, v120, v121
	v_cvt_pk_bf16_f32 v156, v126, v127
	v_cvt_pk_bf16_f32 v157, v128, v129
	s_nop 1
	s_waitcnt lgkmcnt(4)
	v_mfma_f32_16x16x32_bf16 v[0:3], v[146:149], v[162:165], v[0:3]
	v_mfma_f32_16x16x32_bf16 v[32:35], v[154:157], v[162:165], v[32:35]
	ds_read_b64_tr_b16 v[174:175], v209 offset:16384
	ds_read_b64_tr_b16 v[176:177], v209 offset:20480
	v_exp_f32_e32 v130, v130
	v_exp_f32_e32 v131, v131
	v_exp_f32_e32 v132, v132
	v_exp_f32_e32 v133, v133
	v_add_f32_e32 v222, v222, v130
	s_waitcnt lgkmcnt(4)
	v_mfma_f32_16x16x32_bf16 v[36:39], v[154:157], v[166:169], v[36:39]
	v_mfma_f32_16x16x32_bf16 v[4:7], v[146:149], v[166:169], v[4:7]
	ds_read_b64_tr_b16 v[162:163], v210 offset:16384
	ds_read_b64_tr_b16 v[164:165], v210 offset:20480
	v_add_f32_e32 v222, v222, v131
	v_add_f32_e32 v222, v222, v132
	v_add_f32_e32 v222, v222, v133
	v_exp_f32_e32 v138, v138
	v_exp_f32_e32 v139, v139
	s_waitcnt lgkmcnt(4)
; #define SBAR() __builtin_amdgcn_sched_barrier(0)
; __device__ __forceinline__ int crow(int r, int hi) { return (r & 3) + 8 * (r >> 2) + 4 * hi; }
; #define RESC(a) do { if (__any((a) < 1.f)) { if (hi == 0) al_l[r32] = (a); asm volatile("s_waitcnt lgkmcnt(0)" ::: "memory"); \
;     _Pragma("unroll") for (int d = 0; d < 4; ++d) _Pragma("unroll") for (int r = 0; r < 16; ++r) o[d][r] *= al_l[crow(r, hi)]; } } while (0)
; __device__ __forceinline__ void attn_unit(const bf16_t* __restrict__ Qb, const bf16_t* __restrict__ Kn, const bf16_t* __restrict__ Kr, const bf16_t* __restrict__ Vh,
;                                           bf16_t* __restrict__ Ob, char* lds) {
;     ...
;   pv_d0(o, vb0, pa0, pa1, pa2, pa3); partialSM<false>(pB0, pB1, m_reg, alB);
;   __syncthreads(); RESC(alB);
;   finishSM(pB0, pB1, alB, l_reg, pa0, pa1, pa2, pa3); SBAR();
;   pv_d0(o, vb0 + (int)SHM_V, pa0, pa1, pa2, pa3);
;   if (hi == 0) li_l[r32] = l_reg; asm volatile("s_waitcnt lgkmcnt(0)" ::: "memory");
;   float rli[16];
; #pragma unroll
;   for (int r = 0; r < 16; ++r) rli[r] = __builtin_amdgcn_rcpf(li_l[crow(r, hi)]);
	v_mfma_f32_16x16x32_bf16 v[8:11], v[146:149], v[170:173], v[8:11]
	v_mfma_f32_16x16x32_bf16 v[40:43], v[154:157], v[170:173], v[40:43]
	ds_read_b64_tr_b16 v[166:167], v211 offset:16384
	ds_read_b64_tr_b16 v[168:169], v211 offset:20480
	v_exp_f32_e32 v140, v140
	v_exp_f32_e32 v141, v141
	v_add_f32_e32 v222, v222, v138
	v_add_f32_e32 v222, v222, v139
	v_add_f32_e32 v222, v222, v140
	s_waitcnt lgkmcnt(4)
	v_mfma_f32_16x16x32_bf16 v[44:47], v[154:157], v[174:177], v[44:47]
	v_mfma_f32_16x16x32_bf16 v[12:15], v[146:149], v[174:177], v[12:15]
	ds_read_b64_tr_b16 v[170:171], v212 offset:16384
	ds_read_b64_tr_b16 v[172:173], v212 offset:20480
	v_add_f32_e32 v222, v222, v141
	v_cvt_pk_bf16_f32 v150, v130, v131
	v_cvt_pk_bf16_f32 v151, v132, v133
	v_cvt_pk_bf16_f32 v152, v138, v139
	v_cvt_pk_bf16_f32 v153, v140, v141
	s_waitcnt lgkmcnt(4)
	v_mfma_f32_16x16x32_bf16 v[16:19], v[146:149], v[162:165], v[16:19]
	v_mfma_f32_16x16x32_bf16 v[48:51], v[154:157], v[162:165], v[48:51]
	ds_read_b64_tr_b16 v[174:175], v213 offset:16384
	ds_read_b64_tr_b16 v[176:177], v213 offset:20480
	v_exp_f32_e32 v134, v134
	v_exp_f32_e32 v135, v135
	v_exp_f32_e32 v136, v136
	v_exp_f32_e32 v137, v137
	v_add_f32_e32 v223, v223, v134
	s_waitcnt lgkmcnt(4)
	v_mfma_f32_16x16x32_bf16 v[52:55], v[154:157], v[166:169], v[52:55]
	v_mfma_f32_16x16x32_bf16 v[20:23], v[146:149], v[166:169], v[20:23]
	ds_read_b64_tr_b16 v[162:163], v206 offset:24576
	ds_read_b64_tr_b16 v[164:165], v206 offset:28672
	v_add_f32_e32 v223, v223, v135
	v_add_f32_e32 v223, v223, v136
	v_add_f32_e32 v223, v223, v137
	v_exp_f32_e32 v142, v142
	v_exp_f32_e32 v143, v143
	s_waitcnt lgkmcnt(4)
	v_mfma_f32_16x16x32_bf16 v[24:27], v[146:149], v[170:173], v[24:27]
	v_mfma_f32_16x16x32_bf16 v[56:59], v[154:157], v[170:173], v[56:59]
	ds_read_b64_tr_b16 v[166:167], v207 offset:24576
	ds_read_b64_tr_b16 v[168:169], v207 offset:28672
	v_exp_f32_e32 v144, v144
	v_exp_f32_e32 v145, v145
	v_add_f32_e32 v223, v223, v142
	v_add_f32_e32 v223, v223, v143
	v_add_f32_e32 v223, v223, v144
	s_waitcnt lgkmcnt(4)
	v_mfma_f32_16x16x32_bf16 v[60:63], v[154:157], v[174:177], v[60:63]
	v_mfma_f32_16x16x32_bf16 v[28:31], v[146:149], v[174:177], v[28:31]
	ds_read_b64_tr_b16 v[170:171], v208 offset:24576
	ds_read_b64_tr_b16 v[172:173], v208 offset:28672
	v_add_f32_e32 v223, v223, v145
	v_cvt_pk_bf16_f32 v158, v134, v135
	v_cvt_pk_bf16_f32 v159, v136, v137
	v_cvt_pk_bf16_f32 v160, v142, v143
	v_cvt_pk_bf16_f32 v161, v144, v145
	s_waitcnt lgkmcnt(4)
	s_nop 1
	v_mfma_f32_16x16x32_bf16 v[0:3], v[150:153], v[162:165], v[0:3]
	v_mfma_f32_16x16x32_bf16 v[32:35], v[158:161], v[162:165], v[32:35]
	ds_read_b64_tr_b16 v[174:175], v209 offset:24576
	ds_read_b64_tr_b16 v[176:177], v209 offset:28672
	s_waitcnt lgkmcnt(4)
	v_mfma_f32_16x16x32_bf16 v[36:39], v[158:161], v[166:169], v[36:39]
	v_mfma_f32_16x16x32_bf16 v[4:7], v[150:153], v[166:169], v[4:7]
	ds_read_b64_tr_b16 v[162:163], v210 offset:24576
	ds_read_b64_tr_b16 v[164:165], v210 offset:28672
	s_waitcnt lgkmcnt(4)
	v_mfma_f32_16x16x32_bf16 v[8:11], v[150:153], v[170:173], v[8:11]
	v_mfma_f32_16x16x32_bf16 v[40:43], v[158:161], v[170:173], v[40:43]
	ds_read_b64_tr_b16 v[166:167], v211 offset:24576
	ds_read_b64_tr_b16 v[168:169], v211 offset:28672
	s_waitcnt lgkmcnt(4)
	v_mfma_f32_16x16x32_bf16 v[44:47], v[158:161], v[174:177], v[44:47]
	v_mfma_f32_16x16x32_bf16 v[12:15], v[150:153], v[174:177], v[12:15]
	ds_read_b64_tr_b16 v[170:171], v212 offset:24576
	ds_read_b64_tr_b16 v[172:173], v212 offset:28672
	s_waitcnt lgkmcnt(4)
	v_mfma_f32_16x16x32_bf16 v[16:19], v[150:153], v[162:165], v[16:19]
	v_mfma_f32_16x16x32_bf16 v[48:51], v[158:161], v[162:165], v[48:51]
	ds_read_b64_tr_b16 v[174:175], v213 offset:24576
	ds_read_b64_tr_b16 v[176:177], v213 offset:28672
	s_waitcnt lgkmcnt(4)
	v_mfma_f32_16x16x32_bf16 v[52:55], v[158:161], v[166:169], v[52:55]
	v_mfma_f32_16x16x32_bf16 v[20:23], v[150:153], v[166:169], v[20:23]
	s_waitcnt lgkmcnt(2)
	v_mfma_f32_16x16x32_bf16 v[24:27], v[150:153], v[170:173], v[24:27]
	v_mfma_f32_16x16x32_bf16 v[56:59], v[158:161], v[170:173], v[56:59]
	s_waitcnt lgkmcnt(0)
	v_mfma_f32_16x16x32_bf16 v[60:63], v[158:161], v[174:177], v[60:63]
	v_mfma_f32_16x16x32_bf16 v[28:31], v[150:153], v[174:177], v[28:31]
	v_mov_b32_e32 v243, v222
	s_nop 1
	v_permlane32_swap_b32_e32 v222, v243
	s_nop 1
	v_add_f32_e32 v222, v222, v243
	s_nop 1
	ds_bpermute_b32 v243, v112, v222
	s_waitcnt lgkmcnt(0)
	v_add_f32_e32 v222, v222, v243
	v_rcp_f32_e32 v222, v222
	s_nop 0
	ds_write_b32 v219, v222 offset:0
	v_mov_b32_e32 v243, v223
	s_nop 1
	v_permlane32_swap_b32_e32 v223, v243
	s_nop 1
	v_add_f32_e32 v223, v223, v243
	s_nop 1
	ds_bpermute_b32 v243, v112, v223
	s_waitcnt lgkmcnt(0)
	v_add_f32_e32 v223, v223, v243
	v_rcp_f32_e32 v223, v223
	s_nop 0
	ds_write_b32 v219, v223 offset:64
	s_waitcnt lgkmcnt(0)
	v_and_b32_e32 v235, 63, v195
	v_lshrrev_b32_e32 v243, 4, v235
	v_and_b32_e32 v235, 15, v235
	v_lshlrev_b32_e32 v235, 1, v235
	v_lshl_add_u32 v235, v243, 14, v235
	ds_read_b128 v[246:249], v232 offset:0
	s_waitcnt lgkmcnt(0)
; __device__ __forceinline__ unsigned f2bf(float f) { unsigned u = __float_as_uint(f); return (u + 0x7fffu + ((u >> 16) & 1u)) >> 16; }
; __device__ __forceinline__ int crow(int r, int hi) { return (r & 3) + 8 * (r >> 2) + 4 * hi; }
; __device__ __forceinline__ void attn_unit(const bf16_t* __restrict__ Qb, const bf16_t* __restrict__ Kn, const bf16_t* __restrict__ Kr, const bf16_t* __restrict__ Vh,
;                                           bf16_t* __restrict__ Ob, char* lds) {
;     ...
;   bf16_t* Ow = Ob + (long)(wid * 32) * DM;
; #pragma unroll
;   for (int r = 0; r < 16; ++r) { int orow = crow(r, hi);
; #pragma unroll
;     for (int d0 = 0; d0 < 4; ++d0) Ow[(long)orow * DM + d0 * 32 + r32] = (bf16_t)f2bf(o[d0][r] * rli[r]); }
	s_add_u32 s74, s36, 0
	s_addc_u32 s75, s37, 0
	v_mul_f32_e32 v0, v0, v246
	v_mul_f32_e32 v4, v4, v246
	v_cvt_pk_bf16_f32 v0, v0, v4
	s_nop 0
	global_store_short v235, v0, s[74:75] offset:0
	global_store_short_d16_hi v235, v0, s[74:75] offset:32
	v_mul_f32_e32 v8, v8, v246
	v_mul_f32_e32 v12, v12, v246
	v_cvt_pk_bf16_f32 v8, v8, v12
	s_nop 0
	global_store_short v235, v8, s[74:75] offset:64
	global_store_short_d16_hi v235, v8, s[74:75] offset:96
	v_mul_f32_e32 v16, v16, v246
	v_mul_f32_e32 v20, v20, v246
	v_cvt_pk_bf16_f32 v16, v16, v20
	s_nop 0
	global_store_short v235, v16, s[74:75] offset:128
	global_store_short_d16_hi v235, v16, s[74:75] offset:160
	v_mul_f32_e32 v24, v24, v246
	v_mul_f32_e32 v28, v28, v246
	v_cvt_pk_bf16_f32 v24, v24, v28
	s_nop 0
	global_store_short v235, v24, s[74:75] offset:192
	global_store_short_d16_hi v235, v24, s[74:75] offset:224
	s_add_u32 s74, s36, 4096
	s_addc_u32 s75, s37, 0
	v_mul_f32_e32 v1, v1, v247
	v_mul_f32_e32 v5, v5, v247
	v_cvt_pk_bf16_f32 v1, v1, v5
	s_nop 0
	global_store_short v235, v1, s[74:75] offset:0
	global_store_short_d16_hi v235, v1, s[74:75] offset:32
	v_mul_f32_e32 v9, v9, v247
	v_mul_f32_e32 v13, v13, v247
	v_cvt_pk_bf16_f32 v9, v9, v13
	s_nop 0
	global_store_short v235, v9, s[74:75] offset:64
	global_store_short_d16_hi v235, v9, s[74:75] offset:96
	v_mul_f32_e32 v17, v17, v247
	v_mul_f32_e32 v21, v21, v247
	v_cvt_pk_bf16_f32 v17, v17, v21
	s_nop 0
	global_store_short v235, v17, s[74:75] offset:128
	global_store_short_d16_hi v235, v17, s[74:75] offset:160
	v_mul_f32_e32 v25, v25, v247
	v_mul_f32_e32 v29, v29, v247
	v_cvt_pk_bf16_f32 v25, v25, v29
	s_nop 0
	global_store_short v235, v25, s[74:75] offset:192
	global_store_short_d16_hi v235, v25, s[74:75] offset:224
	s_add_u32 s74, s36, 8192
	s_addc_u32 s75, s37, 0
	v_mul_f32_e32 v2, v2, v248
	v_mul_f32_e32 v6, v6, v248
	v_cvt_pk_bf16_f32 v2, v2, v6
	s_nop 0
	global_store_short v235, v2, s[74:75] offset:0
	global_store_short_d16_hi v235, v2, s[74:75] offset:32
	v_mul_f32_e32 v10, v10, v248
	v_mul_f32_e32 v14, v14, v248
	v_cvt_pk_bf16_f32 v10, v10, v14
	s_nop 0
	global_store_short v235, v10, s[74:75] offset:64
	global_store_short_d16_hi v235, v10, s[74:75] offset:96
	v_mul_f32_e32 v18, v18, v248
	v_mul_f32_e32 v22, v22, v248
	v_cvt_pk_bf16_f32 v18, v18, v22
	s_nop 0
	global_store_short v235, v18, s[74:75] offset:128
	global_store_short_d16_hi v235, v18, s[74:75] offset:160
	v_mul_f32_e32 v26, v26, v248
	v_mul_f32_e32 v30, v30, v248
	v_cvt_pk_bf16_f32 v26, v26, v30
	s_nop 0
	global_store_short v235, v26, s[74:75] offset:192
	global_store_short_d16_hi v235, v26, s[74:75] offset:224
	s_add_u32 s74, s36, 12288
	s_addc_u32 s75, s37, 0
	v_mul_f32_e32 v3, v3, v249
	v_mul_f32_e32 v7, v7, v249
	v_cvt_pk_bf16_f32 v3, v3, v7
	s_nop 0
	global_store_short v235, v3, s[74:75] offset:0
	global_store_short_d16_hi v235, v3, s[74:75] offset:32
	v_mul_f32_e32 v11, v11, v249
	v_mul_f32_e32 v15, v15, v249
	v_cvt_pk_bf16_f32 v11, v11, v15
	s_nop 0
	global_store_short v235, v11, s[74:75] offset:64
	global_store_short_d16_hi v235, v11, s[74:75] offset:96
	v_mul_f32_e32 v19, v19, v249
	v_mul_f32_e32 v23, v23, v249
	v_cvt_pk_bf16_f32 v19, v19, v23
	s_nop 0
	global_store_short v235, v19, s[74:75] offset:128
	global_store_short_d16_hi v235, v19, s[74:75] offset:160
	v_mul_f32_e32 v27, v27, v249
	v_mul_f32_e32 v31, v31, v249
	v_cvt_pk_bf16_f32 v27, v27, v31
	s_nop 0
	global_store_short v235, v27, s[74:75] offset:192
	global_store_short_d16_hi v235, v27, s[74:75] offset:224
	ds_read_b128 v[246:249], v232 offset:64
	s_waitcnt lgkmcnt(0)
; __device__ __forceinline__ unsigned f2bf(float f) { unsigned u = __float_as_uint(f); return (u + 0x7fffu + ((u >> 16) & 1u)) >> 16; }
; __device__ __forceinline__ unsigned char* opq(unsigned char* q) { asm volatile("" : "+s"(q)); return q; }
; __device__ __forceinline__ int crow(int r, int hi) { return (r & 3) + 8 * (r >> 2) + 4 * hi; }
; __device__ __forceinline__ void attn_unit(const bf16_t* __restrict__ Qb, const bf16_t* __restrict__ Kn, const bf16_t* __restrict__ Kr, const bf16_t* __restrict__ Vh,
;                                           bf16_t* __restrict__ Ob, char* lds) {
;     ...
;   bf16_t* Ow = Ob + (long)(wid * 32) * DM;
; #pragma unroll
;   for (int r = 0; r < 16; ++r) { int orow = crow(r, hi);
; #pragma unroll
;     for (int d0 = 0; d0 < 4; ++d0) Ow[(long)orow * DM + d0 * 32 + r32] = (bf16_t)f2bf(o[d0][r] * rli[r]); }
;     ...
;   __syncthreads();
; __global__ void __launch_bounds__(512, 2) mega_fwd(KArgs a) {
;     ...
;         { const bool x8 = (G % 8) == 0; const int xcd = bx & 7, slot = bx >> 3, nslot = G >> 3;
;           for (int pr = 0; pr < (x8 ? 2 : 16); ++pr) { const int p = x8 ? xcd + 8 * pr : pr, b = p >> 3, h = p & 7;
;             for (int qb = x8 ? slot : bx; qb < 64; qb += x8 ? nslot : G) {
;               const bf16_t* Qb = (const bf16_t*)(opq(a.ws) + WS_Q) + ((size_t)(b * 8 + h) * T + (size_t)qb * 256) * 192;
;               const bf16_t* Kn = (const bf16_t*)(opq(a.ws) + WS_KN) + (size_t)(b * 8 + h) * T * 128;
;               const bf16_t* Kr = (const bf16_t*)(opq(a.ws) + WS_KR) + (size_t)b * T * 64;
;               const bf16_t* Vh = (const bf16_t*)(opq(a.ws) + WS_V) + (size_t)(b * 8 + h) * T * 128;
;               bf16_t* Ob = (bf16_t*)(opq(a.ws) + WS_XN) + ((size_t)b * T + (size_t)qb * 256) * DM + 1024 + h * 128;
;     ...
;               for (int rep_ = 0; rep_ < PROBE_ATT_REP; ++rep_) att::attn_unit(Qb, Kn, Kr, Vh, Ob, (char*)smem);
	s_add_u32 s74, s36, 65536
	s_addc_u32 s75, s37, 0
	v_mul_f32_e32 v32, v32, v246
	v_mul_f32_e32 v36, v36, v246
	v_cvt_pk_bf16_f32 v32, v32, v36
	s_nop 0
	global_store_short v235, v32, s[74:75] offset:0
	global_store_short_d16_hi v235, v32, s[74:75] offset:32
	v_mul_f32_e32 v40, v40, v246
	v_mul_f32_e32 v44, v44, v246
	v_cvt_pk_bf16_f32 v40, v40, v44
	s_nop 0
	global_store_short v235, v40, s[74:75] offset:64
	global_store_short_d16_hi v235, v40, s[74:75] offset:96
	v_mul_f32_e32 v48, v48, v246
	v_mul_f32_e32 v52, v52, v246
	v_cvt_pk_bf16_f32 v48, v48, v52
	s_nop 0
	global_store_short v235, v48, s[74:75] offset:128
	global_store_short_d16_hi v235, v48, s[74:75] offset:160
	v_mul_f32_e32 v56, v56, v246
	v_mul_f32_e32 v60, v60, v246
	v_cvt_pk_bf16_f32 v56, v56, v60
	s_nop 0
	global_store_short v235, v56, s[74:75] offset:192
	global_store_short_d16_hi v235, v56, s[74:75] offset:224
	s_add_u32 s74, s36, 69632
	s_addc_u32 s75, s37, 0
	v_mul_f32_e32 v33, v33, v247
	v_mul_f32_e32 v37, v37, v247
	v_cvt_pk_bf16_f32 v33, v33, v37
	s_nop 0
	global_store_short v235, v33, s[74:75] offset:0
	global_store_short_d16_hi v235, v33, s[74:75] offset:32
	v_mul_f32_e32 v41, v41, v247
	v_mul_f32_e32 v45, v45, v247
	v_cvt_pk_bf16_f32 v41, v41, v45
	s_nop 0
	global_store_short v235, v41, s[74:75] offset:64
	global_store_short_d16_hi v235, v41, s[74:75] offset:96
	v_mul_f32_e32 v49, v49, v247
	v_mul_f32_e32 v53, v53, v247
	v_cvt_pk_bf16_f32 v49, v49, v53
	s_nop 0
	global_store_short v235, v49, s[74:75] offset:128
	global_store_short_d16_hi v235, v49, s[74:75] offset:160
	v_mul_f32_e32 v57, v57, v247
	v_mul_f32_e32 v61, v61, v247
	v_cvt_pk_bf16_f32 v57, v57, v61
	s_nop 0
	global_store_short v235, v57, s[74:75] offset:192
	global_store_short_d16_hi v235, v57, s[74:75] offset:224
	s_add_u32 s74, s36, 73728
	s_addc_u32 s75, s37, 0
	v_mul_f32_e32 v34, v34, v248
	v_mul_f32_e32 v38, v38, v248
	v_cvt_pk_bf16_f32 v34, v34, v38
	s_nop 0
	global_store_short v235, v34, s[74:75] offset:0
	global_store_short_d16_hi v235, v34, s[74:75] offset:32
	v_mul_f32_e32 v42, v42, v248
	v_mul_f32_e32 v46, v46, v248
	v_cvt_pk_bf16_f32 v42, v42, v46
	s_nop 0
	global_store_short v235, v42, s[74:75] offset:64
	global_store_short_d16_hi v235, v42, s[74:75] offset:96
	v_mul_f32_e32 v50, v50, v248
	v_mul_f32_e32 v54, v54, v248
	v_cvt_pk_bf16_f32 v50, v50, v54
	s_nop 0
	global_store_short v235, v50, s[74:75] offset:128
	global_store_short_d16_hi v235, v50, s[74:75] offset:160
	v_mul_f32_e32 v58, v58, v248
	v_mul_f32_e32 v62, v62, v248
	v_cvt_pk_bf16_f32 v58, v58, v62
	s_nop 0
	global_store_short v235, v58, s[74:75] offset:192
	global_store_short_d16_hi v235, v58, s[74:75] offset:224
	s_add_u32 s74, s36, 77824
	s_addc_u32 s75, s37, 0
	v_mul_f32_e32 v35, v35, v249
	v_mul_f32_e32 v39, v39, v249
	v_cvt_pk_bf16_f32 v35, v35, v39
	s_nop 0
	global_store_short v235, v35, s[74:75] offset:0
	global_store_short_d16_hi v235, v35, s[74:75] offset:32
	v_mul_f32_e32 v43, v43, v249
	v_mul_f32_e32 v47, v47, v249
	v_cvt_pk_bf16_f32 v43, v43, v47
	s_nop 0
	global_store_short v235, v43, s[74:75] offset:64
	global_store_short_d16_hi v235, v43, s[74:75] offset:96
	v_mul_f32_e32 v51, v51, v249
	v_mul_f32_e32 v55, v55, v249
	v_cvt_pk_bf16_f32 v51, v51, v55
	s_nop 0
	global_store_short v235, v51, s[74:75] offset:128
	global_store_short_d16_hi v235, v51, s[74:75] offset:160
	v_mul_f32_e32 v59, v59, v249
	v_mul_f32_e32 v63, v63, v249
	v_cvt_pk_bf16_f32 v59, v59, v63
	s_nop 0
	global_store_short v235, v59, s[74:75] offset:192
	global_store_short_d16_hi v235, v59, s[74:75] offset:224
	v_bfrev_b32_e32 v236, 0.5
	v_mbcnt_lo_u32_b32 v237, -1, 0
	v_mov_b32_e32 v238, 0x41b17218
	v_mov_b32_e32 v239, 1
	v_mov_b64_e32 v[240:241], 0x400
	v_mov_b32_e32 v242, 0x3000
	v_mbcnt_hi_u32_b32 v237, -1, v237
	s_waitcnt vmcnt(0)
	v_readlane_b32 s6, v254, 15
	s_add_i32 s16, s16, s6
	s_cmp_gt_i32 s16, 63
	s_waitcnt lgkmcnt(0)
	s_barrier
	s_cbranch_scc1 .LBB0_462
	s_branch .LBB0_466
